# GEMM K-loops (6 sites): loop-carried SALU block (counter/pointer advance, stage select) moved from the back-edge head into phase 4's load segment before its vmcnt wait
# speedup vs baseline: 1.0012x; 1.0002x over previous
; #define PG8_STAGE(bufoff, gbase, voff) do { _Pragma("unroll") for (int _i = 0; _i < 2; ++_i) \
;         __builtin_amdgcn_global_load_lds((const unsigned*)((const char*)(gbase) + (voff)[_i]), (PG8_LAS unsigned*)(lds + (bufoff) + ldsw + _i * 8192), 16, 0, 0); } while (0)
; #define PG8_LDA(dst, b, h) do { _Pragma("unroll") for (int m = 0; m < 4; ++m) _Pragma("unroll") for (int k = 0; k < 2; ++k) dst[m][k] = *(const PG8_LAS bf16x8*)(lds + PG8_SA(b, h) + aoff + m * 2048 + k * 1024); } while (0)
; #define PG8_LDB(dst, b, h) do { _Pragma("unroll") for (int n = 0; n < 2; ++n) _Pragma("unroll") for (int k = 0; k < 2; ++k) dst[n][k] = *(const PG8_LAS bf16x8*)(lds + PG8_SB(b, h) + boff + n * 2048 + k * 1024); } while (0)
; #define PG8_WAIT_V(n) asm volatile("s_waitcnt vmcnt(" #n ")" ::: "memory")
; #define PG8_WAIT_L(n) asm volatile("s_waitcnt lgkmcnt(" #n ")" ::: "memory")
; #define PG8_BAR __builtin_amdgcn_s_barrier()
; #define PG8_SCHED __builtin_amdgcn_sched_barrier(0)
; template <class Epi, bool ALIGN_EPI = true>
; __device__ __forceinline__ void gemm_phase(PG8_LAS unsigned char* lds, const Gemm g, const StaticOrder& S, const Epi& E) {
;     ...
;             PG8_LDB(B0, 0, 0); PG8_LDB(B1, 0, 1); PG8_SCHED; PG8_LDA(At, 0, 0); PG8_STAGE(PG8_SA(1, 1), a1 + hstepA, voffA);
;             PG8_WAIT_V(8); PG8_WAIT_L(0); PG8_BAR; PG8_MMA(0, 0, At, B0); PG8_MMA(0, 1, At, B1); PG8_BAR; PG8_SCHED;
;             PG8_LDA(At, 0, 1); PG8_STAGE(PG8_SB(0, 0), b2, voffB); PG8_STAGE(PG8_SB(0, 1), b2 + hstepB, voffB); PG8_STAGE(PG8_SA(0, 0), a2, voffA);
;             PG8_WAIT_V(8); PG8_WAIT_L(0); PG8_BAR; PG8_MMA(1, 0, At, B0); PG8_MMA(1, 1, At, B1); PG8_BAR; PG8_SCHED;
.Lrot_439:
	ds_read_b128 v[142:145], v32
	ds_read_b128 v[148:151], v32 offset:1024
	ds_read_b128 v[158:161], v32 offset:2048
	ds_read_b128 v[168:171], v32 offset:3072
	v_add_u32_e32 v32, s56, v164
	ds_read_b128 v[172:175], v32
	ds_read_b128 v[176:179], v32 offset:1024
	ds_read_b128 v[180:183], v32 offset:2048
	ds_read_b128 v[184:187], v32 offset:3072
	v_lshl_add_u64 v[146:147], s[8:9], 0, v[138:139]
	s_add_i32 m0, s41, 0xc000
	ds_read_b128 v[188:191], v166
	ds_read_b128 v[192:195], v166 offset:1024
	ds_read_b128 v[196:199], v166 offset:2048
	ds_read_b128 v[208:211], v166 offset:3072
	ds_read_b128 v[216:219], v166 offset:4096
	ds_read_b128 v[220:223], v166 offset:5120
	ds_read_b128 v[224:227], v166 offset:6144
	ds_read_b128 v[228:231], v166 offset:7168
	global_load_lds_dwordx4 v[146:147], off
	v_lshl_add_u64 v[146:147], s[8:9], 0, v[140:141]
	s_add_i32 m0, s41, 0xe000
	s_nop 0
	global_load_lds_dwordx4 v[146:147], off
	s_waitcnt vmcnt(8)
	s_waitcnt lgkmcnt(0)
	s_barrier
	s_setprio 1
	s_waitcnt lgkmcnt(0)
	v_mfma_f32_16x16x32_bf16 v[126:129], v[142:145], v[188:191], v[126:129]
	v_mfma_f32_16x16x32_bf16 v[122:125], v[158:161], v[188:191], v[122:125]
	v_mfma_f32_16x16x32_bf16 v[110:113], v[142:145], v[196:199], v[110:113]
	v_mfma_f32_16x16x32_bf16 v[106:109], v[158:161], v[196:199], v[106:109]
	v_mfma_f32_16x16x32_bf16 v[94:97], v[142:145], v[216:219], v[94:97]
	v_mfma_f32_16x16x32_bf16 v[90:93], v[158:161], v[216:219], v[90:93]
	v_mfma_f32_16x16x32_bf16 v[78:81], v[142:145], v[224:227], v[78:81]
	v_mfma_f32_16x16x32_bf16 v[74:77], v[158:161], v[224:227], v[74:77]
	v_mfma_f32_16x16x32_bf16 v[126:129], v[148:151], v[192:195], v[126:129]
	v_mfma_f32_16x16x32_bf16 v[122:125], v[168:171], v[192:195], v[122:125]
	v_mfma_f32_16x16x32_bf16 v[110:113], v[148:151], v[208:211], v[110:113]
	v_mfma_f32_16x16x32_bf16 v[106:109], v[168:171], v[208:211], v[106:109]
	v_mfma_f32_16x16x32_bf16 v[94:97], v[148:151], v[220:223], v[94:97]
	v_mfma_f32_16x16x32_bf16 v[90:93], v[168:171], v[220:223], v[90:93]
	v_mfma_f32_16x16x32_bf16 v[78:81], v[148:151], v[228:231], v[78:81]
	v_mfma_f32_16x16x32_bf16 v[74:77], v[168:171], v[228:231], v[74:77]
	s_setprio 0
	s_setprio 1
	v_mfma_f32_16x16x32_bf16 v[118:121], v[172:175], v[188:191], v[118:121]
	v_mfma_f32_16x16x32_bf16 v[114:117], v[180:183], v[188:191], v[114:117]
	v_mfma_f32_16x16x32_bf16 v[102:105], v[172:175], v[196:199], v[102:105]
	v_mfma_f32_16x16x32_bf16 v[98:101], v[180:183], v[196:199], v[98:101]
	v_mfma_f32_16x16x32_bf16 v[86:89], v[172:175], v[216:219], v[86:89]
	v_mfma_f32_16x16x32_bf16 v[82:85], v[180:183], v[216:219], v[82:85]
	v_mfma_f32_16x16x32_bf16 v[70:73], v[172:175], v[224:227], v[70:73]
	v_mfma_f32_16x16x32_bf16 v[66:69], v[180:183], v[224:227], v[66:69]
	v_mfma_f32_16x16x32_bf16 v[118:121], v[176:179], v[192:195], v[118:121]
	v_mfma_f32_16x16x32_bf16 v[114:117], v[184:187], v[192:195], v[114:117]
	v_mfma_f32_16x16x32_bf16 v[102:105], v[176:179], v[208:211], v[102:105]
	v_mfma_f32_16x16x32_bf16 v[98:101], v[184:187], v[208:211], v[98:101]
	v_mfma_f32_16x16x32_bf16 v[86:89], v[176:179], v[220:223], v[86:89]
	v_mfma_f32_16x16x32_bf16 v[82:85], v[184:187], v[220:223], v[82:85]
	v_mfma_f32_16x16x32_bf16 v[70:73], v[176:179], v[228:231], v[70:73]
	v_mfma_f32_16x16x32_bf16 v[66:69], v[184:187], v[228:231], v[66:69]
	s_setprio 0
	s_barrier
	s_add_i32 s53, s53, s40
	v_lshl_add_u64 v[146:147], s[28:29], 0, v[132:133]
	s_mov_b32 m0, s53
	ds_read_b128 v[188:191], v166 offset:16384
	ds_read_b128 v[192:195], v166 offset:17408
	ds_read_b128 v[196:199], v166 offset:18432
	ds_read_b128 v[208:211], v166 offset:19456
	ds_read_b128 v[216:219], v166 offset:20480
	ds_read_b128 v[220:223], v166 offset:21504
	ds_read_b128 v[224:227], v166 offset:22528
	ds_read_b128 v[228:231], v166 offset:23552
	global_load_lds_dwordx4 v[146:147], off
	s_add_i32 m0, s53, 0x2000
	s_add_u32 s58, s28, 0x40000
	v_lshl_add_u64 v[200:201], s[28:29], 0, v[136:137]
	s_addc_u32 s59, s29, 0
	s_add_i32 s53, s56, s40
	global_load_lds_dwordx4 v[200:201], off
	v_lshl_add_u64 v[204:205], s[58:59], 0, v[132:133]
	s_mov_b32 m0, s53
	v_lshl_add_u64 v[206:207], s[30:31], 0, v[134:135]
	global_load_lds_dwordx4 v[204:205], off
	v_lshl_add_u64 v[204:205], s[58:59], 0, v[136:137]
	s_add_i32 m0, s53, 0x2000
	s_nop 0
	global_load_lds_dwordx4 v[204:205], off
	v_lshl_add_u64 v[204:205], s[30:31], 0, v[130:131]
	s_mov_b32 m0, s41
	s_nop 0
	global_load_lds_dwordx4 v[204:205], off
	s_mov_b32 m0, s42
	s_nop 0
	global_load_lds_dwordx4 v[206:207], off
	s_waitcnt vmcnt(8)
	s_waitcnt lgkmcnt(0)
	s_barrier
; #define PG8_STAGE(bufoff, gbase, voff) do { _Pragma("unroll") for (int _i = 0; _i < 2; ++_i) \
;         __builtin_amdgcn_global_load_lds((const unsigned*)((const char*)(gbase) + (voff)[_i]), (PG8_LAS unsigned*)(lds + (bufoff) + ldsw + _i * 8192), 16, 0, 0); } while (0)
; #define PG8_LDA(dst, b, h) do { _Pragma("unroll") for (int m = 0; m < 4; ++m) _Pragma("unroll") for (int k = 0; k < 2; ++k) dst[m][k] = *(const PG8_LAS bf16x8*)(lds + PG8_SA(b, h) + aoff + m * 2048 + k * 1024); } while (0)
; #define PG8_LDB(dst, b, h) do { _Pragma("unroll") for (int n = 0; n < 2; ++n) _Pragma("unroll") for (int k = 0; k < 2; ++k) dst[n][k] = *(const PG8_LAS bf16x8*)(lds + PG8_SB(b, h) + boff + n * 2048 + k * 1024); } while (0)
; #define PG8_WAIT_V(n) asm volatile("s_waitcnt vmcnt(" #n ")" ::: "memory")
; #define PG8_WAIT_L(n) asm volatile("s_waitcnt lgkmcnt(" #n ")" ::: "memory")
; #define PG8_BAR __builtin_amdgcn_s_barrier()
; #define PG8_SCHED __builtin_amdgcn_sched_barrier(0)
; template <class Epi, bool ALIGN_EPI = true>
; __device__ __forceinline__ void gemm_phase(PG8_LAS unsigned char* lds, const Gemm g, const StaticOrder& S, const Epi& E) {
;     ...
;             PG8_WAIT_V(8); PG8_WAIT_L(0); PG8_BAR; PG8_MMA(1, 0, At, B0); PG8_MMA(1, 1, At, B1); PG8_BAR; PG8_SCHED;
;             PG8_LDB(B0, 1, 0); PG8_LDB(B1, 1, 1); PG8_SCHED; PG8_LDA(At, 1, 0); PG8_STAGE(PG8_SA(0, 1), a2 + hstepA, voffA);
;             PG8_WAIT_V(8); PG8_WAIT_L(0); PG8_BAR; PG8_MMA(0, 0, At, B0); PG8_MMA(0, 1, At, B1); PG8_BAR; PG8_SCHED;
	s_setprio 1
	s_waitcnt lgkmcnt(0)
	v_mfma_f32_16x16x32_bf16 v[62:65], v[142:145], v[188:191], v[62:65]
	v_mfma_f32_16x16x32_bf16 v[58:61], v[158:161], v[188:191], v[58:61]
	v_mfma_f32_16x16x32_bf16 v[46:49], v[142:145], v[196:199], v[46:49]
	v_mfma_f32_16x16x32_bf16 v[42:45], v[158:161], v[196:199], v[42:45]
	v_mfma_f32_16x16x32_bf16 v[28:31], v[142:145], v[216:219], v[28:31]
	v_mfma_f32_16x16x32_bf16 v[24:27], v[158:161], v[216:219], v[24:27]
	v_mfma_f32_16x16x32_bf16 v[12:15], v[142:145], v[224:227], v[12:15]
	v_mfma_f32_16x16x32_bf16 v[8:11], v[158:161], v[224:227], v[8:11]
	v_mfma_f32_16x16x32_bf16 v[62:65], v[148:151], v[192:195], v[62:65]
	v_mfma_f32_16x16x32_bf16 v[58:61], v[168:171], v[192:195], v[58:61]
	v_mfma_f32_16x16x32_bf16 v[46:49], v[148:151], v[208:211], v[46:49]
	v_mfma_f32_16x16x32_bf16 v[42:45], v[168:171], v[208:211], v[42:45]
	v_mfma_f32_16x16x32_bf16 v[28:31], v[148:151], v[220:223], v[28:31]
	v_mfma_f32_16x16x32_bf16 v[24:27], v[168:171], v[220:223], v[24:27]
	v_mfma_f32_16x16x32_bf16 v[12:15], v[148:151], v[228:231], v[12:15]
	v_mfma_f32_16x16x32_bf16 v[8:11], v[168:171], v[228:231], v[8:11]
	s_setprio 0
	s_setprio 1
	v_mfma_f32_16x16x32_bf16 v[54:57], v[172:175], v[188:191], v[54:57]
	v_mfma_f32_16x16x32_bf16 v[50:53], v[180:183], v[188:191], v[50:53]
	v_mfma_f32_16x16x32_bf16 v[38:41], v[172:175], v[196:199], v[38:41]
	v_mfma_f32_16x16x32_bf16 v[34:37], v[180:183], v[196:199], v[34:37]
	v_mfma_f32_16x16x32_bf16 v[20:23], v[172:175], v[216:219], v[20:23]
	v_mfma_f32_16x16x32_bf16 v[16:19], v[180:183], v[216:219], v[16:19]
	v_mfma_f32_16x16x32_bf16 v[4:7], v[172:175], v[224:227], v[4:7]
	v_mfma_f32_16x16x32_bf16 v[0:3], v[180:183], v[224:227], v[0:3]
	v_mfma_f32_16x16x32_bf16 v[54:57], v[176:179], v[192:195], v[54:57]
	v_mfma_f32_16x16x32_bf16 v[50:53], v[184:187], v[192:195], v[50:53]
	v_mfma_f32_16x16x32_bf16 v[38:41], v[176:179], v[208:211], v[38:41]
	v_mfma_f32_16x16x32_bf16 v[34:37], v[184:187], v[208:211], v[34:37]
	v_mfma_f32_16x16x32_bf16 v[20:23], v[176:179], v[220:223], v[20:23]
	v_mfma_f32_16x16x32_bf16 v[16:19], v[184:187], v[220:223], v[16:19]
	v_mfma_f32_16x16x32_bf16 v[4:7], v[176:179], v[228:231], v[4:7]
	v_mfma_f32_16x16x32_bf16 v[0:3], v[184:187], v[228:231], v[0:3]
	s_setprio 0
	s_barrier
	s_add_i32 s53, 0, 0x18000
	v_add_u32_e32 v32, s53, v164
	s_add_i32 s56, 0, 0x1c000
	ds_read_b128 v[142:145], v32
	ds_read_b128 v[148:151], v32 offset:1024
	ds_read_b128 v[158:161], v32 offset:2048
	ds_read_b128 v[168:171], v32 offset:3072
	v_add_u32_e32 v32, s56, v164
	ds_read_b128 v[172:175], v32
	ds_read_b128 v[176:179], v32 offset:1024
	ds_read_b128 v[180:183], v32 offset:2048
	ds_read_b128 v[184:187], v32 offset:3072
	s_add_u32 s30, s30, 0x40000
	s_addc_u32 s31, s31, 0
	s_mov_b32 m0, s43
	v_lshl_add_u64 v[232:233], s[30:31], 0, v[130:131]
	ds_read_b128 v[188:191], v166 offset:32768
	ds_read_b128 v[192:195], v166 offset:33792
	ds_read_b128 v[196:199], v166 offset:34816
	ds_read_b128 v[208:211], v166 offset:35840
	ds_read_b128 v[216:219], v166 offset:36864
	ds_read_b128 v[220:223], v166 offset:37888
	ds_read_b128 v[224:227], v166 offset:38912
	ds_read_b128 v[228:231], v166 offset:39936
	global_load_lds_dwordx4 v[232:233], off
	v_lshl_add_u64 v[232:233], s[30:31], 0, v[134:135]
	s_mov_b32 m0, s44
	s_nop 0
	global_load_lds_dwordx4 v[232:233], off
	s_waitcnt vmcnt(8)
	s_waitcnt lgkmcnt(0)
	s_barrier
	s_setprio 1
	s_waitcnt lgkmcnt(0)
	v_mfma_f32_16x16x32_bf16 v[126:129], v[142:145], v[188:191], v[126:129]
	v_mfma_f32_16x16x32_bf16 v[122:125], v[158:161], v[188:191], v[122:125]
	v_mfma_f32_16x16x32_bf16 v[110:113], v[142:145], v[196:199], v[110:113]
	v_mfma_f32_16x16x32_bf16 v[106:109], v[158:161], v[196:199], v[106:109]
	v_mfma_f32_16x16x32_bf16 v[94:97], v[142:145], v[216:219], v[94:97]
	v_mfma_f32_16x16x32_bf16 v[90:93], v[158:161], v[216:219], v[90:93]
	v_mfma_f32_16x16x32_bf16 v[78:81], v[142:145], v[224:227], v[78:81]
	v_mfma_f32_16x16x32_bf16 v[74:77], v[158:161], v[224:227], v[74:77]
	v_mfma_f32_16x16x32_bf16 v[126:129], v[148:151], v[192:195], v[126:129]
	v_mfma_f32_16x16x32_bf16 v[122:125], v[168:171], v[192:195], v[122:125]
	v_mfma_f32_16x16x32_bf16 v[110:113], v[148:151], v[208:211], v[110:113]
	v_mfma_f32_16x16x32_bf16 v[106:109], v[168:171], v[208:211], v[106:109]
	v_mfma_f32_16x16x32_bf16 v[94:97], v[148:151], v[220:223], v[94:97]
	v_mfma_f32_16x16x32_bf16 v[90:93], v[168:171], v[220:223], v[90:93]
	v_mfma_f32_16x16x32_bf16 v[78:81], v[148:151], v[228:231], v[78:81]
	v_mfma_f32_16x16x32_bf16 v[74:77], v[168:171], v[228:231], v[74:77]
	s_setprio 0
	s_setprio 1
	v_mfma_f32_16x16x32_bf16 v[118:121], v[172:175], v[188:191], v[118:121]
	v_mfma_f32_16x16x32_bf16 v[114:117], v[180:183], v[188:191], v[114:117]
	v_mfma_f32_16x16x32_bf16 v[102:105], v[172:175], v[196:199], v[102:105]
	v_mfma_f32_16x16x32_bf16 v[98:101], v[180:183], v[196:199], v[98:101]
	v_mfma_f32_16x16x32_bf16 v[86:89], v[172:175], v[216:219], v[86:89]
	v_mfma_f32_16x16x32_bf16 v[82:85], v[180:183], v[216:219], v[82:85]
	v_mfma_f32_16x16x32_bf16 v[70:73], v[172:175], v[224:227], v[70:73]
	v_mfma_f32_16x16x32_bf16 v[66:69], v[180:183], v[224:227], v[66:69]
	v_mfma_f32_16x16x32_bf16 v[118:121], v[176:179], v[192:195], v[118:121]
	v_mfma_f32_16x16x32_bf16 v[114:117], v[184:187], v[192:195], v[114:117]
	v_mfma_f32_16x16x32_bf16 v[102:105], v[176:179], v[208:211], v[102:105]
	v_mfma_f32_16x16x32_bf16 v[98:101], v[184:187], v[208:211], v[98:101]
	v_mfma_f32_16x16x32_bf16 v[86:89], v[176:179], v[220:223], v[86:89]
	v_mfma_f32_16x16x32_bf16 v[82:85], v[184:187], v[220:223], v[82:85]
	v_mfma_f32_16x16x32_bf16 v[70:73], v[176:179], v[228:231], v[70:73]
	v_mfma_f32_16x16x32_bf16 v[66:69], v[184:187], v[228:231], v[66:69]
	s_setprio 0
	s_barrier
; #define PG8_STAGE(bufoff, gbase, voff) do { _Pragma("unroll") for (int _i = 0; _i < 2; ++_i) \
;         __builtin_amdgcn_global_load_lds((const unsigned*)((const char*)(gbase) + (voff)[_i]), (PG8_LAS unsigned*)(lds + (bufoff) + ldsw + _i * 8192), 16, 0, 0); } while (0)
; #define PG8_LDA(dst, b, h) do { _Pragma("unroll") for (int m = 0; m < 4; ++m) _Pragma("unroll") for (int k = 0; k < 2; ++k) dst[m][k] = *(const PG8_LAS bf16x8*)(lds + PG8_SA(b, h) + aoff + m * 2048 + k * 1024); } while (0)
; #define PG8_WAIT_V(n) asm volatile("s_waitcnt vmcnt(" #n ")" ::: "memory")
; #define PG8_WAIT_L(n) asm volatile("s_waitcnt lgkmcnt(" #n ")" ::: "memory")
; #define PG8_BAR __builtin_amdgcn_s_barrier()
; #define PG8_SCHED __builtin_amdgcn_sched_barrier(0)
; template <class Epi, bool ALIGN_EPI = true>
; __device__ __forceinline__ void gemm_phase(PG8_LAS unsigned char* lds, const Gemm g, const StaticOrder& S, const Epi& E) {
;     ...
;             PG8_LDA(At, 1, 1); PG8_STAGE(PG8_SB(1, 0), b3, voffB); PG8_STAGE(PG8_SB(1, 1), b3 + hstepB, voffB); PG8_STAGE(PG8_SA(1, 0), a3, voffA);
;             PG8_WAIT_V(8); PG8_WAIT_L(0); PG8_BAR; PG8_MMA(1, 0, At, B0); PG8_MMA(1, 1, At, B1); PG8_BAR; PG8_SCHED;
	s_add_i32 s30, s53, s40
	v_lshl_add_u64 v[146:147], v[146:147], 0, s[60:61]
	s_mov_b32 m0, s30
	ds_read_b128 v[188:191], v166 offset:49152
	ds_read_b128 v[192:195], v166 offset:50176
	ds_read_b128 v[196:199], v166 offset:51200
	ds_read_b128 v[208:211], v166 offset:52224
	ds_read_b128 v[216:219], v166 offset:53248
	ds_read_b128 v[220:223], v166 offset:54272
	ds_read_b128 v[224:227], v166 offset:55296
	ds_read_b128 v[228:231], v166 offset:56320
	global_load_lds_dwordx4 v[146:147], off
	s_add_i32 m0, s30, 0x2000
	s_add_u32 s28, s28, 0x40080
	v_lshl_add_u64 v[146:147], v[200:201], 0, s[60:61]
	s_addc_u32 s29, s29, 0
	s_add_i32 s30, s56, s40
	global_load_lds_dwordx4 v[146:147], off
	v_lshl_add_u64 v[146:147], s[28:29], 0, v[132:133]
	s_mov_b32 m0, s30
	s_nop 0
	global_load_lds_dwordx4 v[146:147], off
	v_lshl_add_u64 v[146:147], s[28:29], 0, v[136:137]
	s_add_i32 m0, s30, 0x2000
	s_nop 0
	global_load_lds_dwordx4 v[146:147], off
	v_lshl_add_u64 v[146:147], v[204:205], 0, s[60:61]
	s_mov_b32 m0, s45
	s_nop 0
	global_load_lds_dwordx4 v[146:147], off
	v_lshl_add_u64 v[146:147], v[206:207], 0, s[60:61]
	s_mov_b32 m0, s46
	s_nop 0
	global_load_lds_dwordx4 v[146:147], off
	s_add_i32 s52, s52, 2
	s_add_u32 s8, s8, 0x100
	s_addc_u32 s9, s9, 0
	s_add_u32 s50, s50, 0x100
	s_addc_u32 s51, s51, 0
	s_add_u32 s28, s8, 0xfffc0080
	s_addc_u32 s29, s9, -1
	s_add_i32 s53, 0, 0x10000
	s_cmp_eq_u32 s52, 12
	s_cselect_b32 s31, s3, s29
	s_cselect_b32 s30, s7, s28
	v_add_u32_e32 v32, s53, v164
	s_cselect_b32 s29, s21, s51
	s_cselect_b32 s28, s23, s50
	s_add_i32 s56, 0, 0x14000
	s_cmp_gt_u32 s52, 13
	s_waitcnt vmcnt(8)
	s_waitcnt lgkmcnt(0)
	s_barrier
	s_setprio 1
	s_waitcnt lgkmcnt(0)
	v_mfma_f32_16x16x32_bf16 v[62:65], v[142:145], v[188:191], v[62:65]
	v_mfma_f32_16x16x32_bf16 v[58:61], v[158:161], v[188:191], v[58:61]
	v_mfma_f32_16x16x32_bf16 v[46:49], v[142:145], v[196:199], v[46:49]
	v_mfma_f32_16x16x32_bf16 v[42:45], v[158:161], v[196:199], v[42:45]
	v_mfma_f32_16x16x32_bf16 v[28:31], v[142:145], v[216:219], v[28:31]
	v_mfma_f32_16x16x32_bf16 v[24:27], v[158:161], v[216:219], v[24:27]
	v_mfma_f32_16x16x32_bf16 v[12:15], v[142:145], v[224:227], v[12:15]
	v_mfma_f32_16x16x32_bf16 v[8:11], v[158:161], v[224:227], v[8:11]
	v_mfma_f32_16x16x32_bf16 v[62:65], v[148:151], v[192:195], v[62:65]
	v_mfma_f32_16x16x32_bf16 v[58:61], v[168:171], v[192:195], v[58:61]
	v_mfma_f32_16x16x32_bf16 v[46:49], v[148:151], v[208:211], v[46:49]
	v_mfma_f32_16x16x32_bf16 v[42:45], v[168:171], v[208:211], v[42:45]
	v_mfma_f32_16x16x32_bf16 v[28:31], v[148:151], v[220:223], v[28:31]
	v_mfma_f32_16x16x32_bf16 v[24:27], v[168:171], v[220:223], v[24:27]
	v_mfma_f32_16x16x32_bf16 v[12:15], v[148:151], v[228:231], v[12:15]
	v_mfma_f32_16x16x32_bf16 v[8:11], v[168:171], v[228:231], v[8:11]
	s_setprio 0
	s_setprio 1
	v_mfma_f32_16x16x32_bf16 v[54:57], v[172:175], v[188:191], v[54:57]
	v_mfma_f32_16x16x32_bf16 v[50:53], v[180:183], v[188:191], v[50:53]
	v_mfma_f32_16x16x32_bf16 v[38:41], v[172:175], v[196:199], v[38:41]
	v_mfma_f32_16x16x32_bf16 v[34:37], v[180:183], v[196:199], v[34:37]
	v_mfma_f32_16x16x32_bf16 v[20:23], v[172:175], v[216:219], v[20:23]
	v_mfma_f32_16x16x32_bf16 v[16:19], v[180:183], v[216:219], v[16:19]
	v_mfma_f32_16x16x32_bf16 v[4:7], v[172:175], v[224:227], v[4:7]
	v_mfma_f32_16x16x32_bf16 v[0:3], v[180:183], v[224:227], v[0:3]
	v_mfma_f32_16x16x32_bf16 v[54:57], v[176:179], v[192:195], v[54:57]
	v_mfma_f32_16x16x32_bf16 v[50:53], v[184:187], v[192:195], v[50:53]
	v_mfma_f32_16x16x32_bf16 v[38:41], v[176:179], v[208:211], v[38:41]
	v_mfma_f32_16x16x32_bf16 v[34:37], v[184:187], v[208:211], v[34:37]
	v_mfma_f32_16x16x32_bf16 v[20:23], v[176:179], v[220:223], v[20:23]
	v_mfma_f32_16x16x32_bf16 v[16:19], v[184:187], v[220:223], v[16:19]
	v_mfma_f32_16x16x32_bf16 v[4:7], v[176:179], v[228:231], v[4:7]
	v_mfma_f32_16x16x32_bf16 v[0:3], v[184:187], v[228:231], v[0:3]
	s_setprio 0
	s_barrier
	s_cbranch_scc0 .Lrot_439
	s_and_b64 vcc, exec, s[18:19]
	s_cbranch_vccz .LBB0_442
	s_barrier

; #define PG8_STAGE(bufoff, gbase, voff) do { _Pragma("unroll") for (int _i = 0; _i < 2; ++_i) \
;         __builtin_amdgcn_global_load_lds((const unsigned*)((const char*)(gbase) + (voff)[_i]), (PG8_LAS unsigned*)(lds + (bufoff) + ldsw + _i * 8192), 16, 0, 0); } while (0)
; #define PG8_LDA(dst, b, h) do { _Pragma("unroll") for (int m = 0; m < 4; ++m) _Pragma("unroll") for (int k = 0; k < 2; ++k) dst[m][k] = *(const PG8_LAS bf16x8*)(lds + PG8_SA(b, h) + aoff + m * 2048 + k * 1024); } while (0)
; #define PG8_LDB(dst, b, h) do { _Pragma("unroll") for (int n = 0; n < 2; ++n) _Pragma("unroll") for (int k = 0; k < 2; ++k) dst[n][k] = *(const PG8_LAS bf16x8*)(lds + PG8_SB(b, h) + boff + n * 2048 + k * 1024); } while (0)
; #define PG8_WAIT_V(n) asm volatile("s_waitcnt vmcnt(" #n ")" ::: "memory")
; #define PG8_WAIT_L(n) asm volatile("s_waitcnt lgkmcnt(" #n ")" ::: "memory")
; #define PG8_BAR __builtin_amdgcn_s_barrier()
; #define PG8_SCHED __builtin_amdgcn_sched_barrier(0)
; template <class Epi, bool ALIGN_EPI = true>
; __device__ __forceinline__ void gemm_phase(PG8_LAS unsigned char* lds, const Gemm g, const StaticOrder& S, const Epi& E) {
;     ...
;             PG8_LDB(B0, 0, 0); PG8_LDB(B1, 0, 1); PG8_SCHED; PG8_LDA(At, 0, 0); PG8_STAGE(PG8_SA(1, 1), a1 + hstepA, voffA);
;             PG8_WAIT_V(8); PG8_WAIT_L(0); PG8_BAR; PG8_MMA(0, 0, At, B0); PG8_MMA(0, 1, At, B1); PG8_BAR; PG8_SCHED;
;             PG8_LDA(At, 0, 1); PG8_STAGE(PG8_SB(0, 0), b2, voffB); PG8_STAGE(PG8_SB(0, 1), b2 + hstepB, voffB); PG8_STAGE(PG8_SA(0, 0), a2, voffA);
;             PG8_WAIT_V(8); PG8_WAIT_L(0); PG8_BAR; PG8_MMA(1, 0, At, B0); PG8_MMA(1, 1, At, B1); PG8_BAR; PG8_SCHED;
.Lrot_795:
	ds_read_b128 v[142:145], v32
	ds_read_b128 v[148:151], v32 offset:1024
	ds_read_b128 v[158:161], v32 offset:2048
	ds_read_b128 v[168:171], v32 offset:3072
	v_add_u32_e32 v32, s43, v165
	ds_read_b128 v[172:175], v32
	ds_read_b128 v[176:179], v32 offset:1024
	ds_read_b128 v[180:183], v32 offset:2048
	ds_read_b128 v[184:187], v32 offset:3072
	v_lshl_add_u64 v[146:147], s[6:7], 0, v[138:139]
	s_add_i32 m0, s59, 0xc000
	ds_read_b128 v[188:191], v167
	ds_read_b128 v[192:195], v167 offset:1024
	ds_read_b128 v[196:199], v167 offset:2048
	ds_read_b128 v[208:211], v167 offset:3072
	ds_read_b128 v[216:219], v167 offset:4096
	ds_read_b128 v[220:223], v167 offset:5120
	ds_read_b128 v[224:227], v167 offset:6144
	ds_read_b128 v[228:231], v167 offset:7168
	global_load_lds_dwordx4 v[146:147], off
	v_lshl_add_u64 v[146:147], s[6:7], 0, v[140:141]
	s_add_i32 m0, s59, 0xe000
	s_nop 0
	global_load_lds_dwordx4 v[146:147], off
	s_waitcnt vmcnt(8)
	s_waitcnt lgkmcnt(0)
	s_barrier
	s_setprio 1
	s_waitcnt lgkmcnt(0)
	v_mfma_f32_16x16x32_bf16 v[126:129], v[142:145], v[188:191], v[126:129]
	v_mfma_f32_16x16x32_bf16 v[122:125], v[158:161], v[188:191], v[122:125]
	v_mfma_f32_16x16x32_bf16 v[110:113], v[142:145], v[196:199], v[110:113]
	v_mfma_f32_16x16x32_bf16 v[106:109], v[158:161], v[196:199], v[106:109]
	v_mfma_f32_16x16x32_bf16 v[94:97], v[142:145], v[216:219], v[94:97]
	v_mfma_f32_16x16x32_bf16 v[90:93], v[158:161], v[216:219], v[90:93]
	v_mfma_f32_16x16x32_bf16 v[78:81], v[142:145], v[224:227], v[78:81]
	v_mfma_f32_16x16x32_bf16 v[74:77], v[158:161], v[224:227], v[74:77]
	v_mfma_f32_16x16x32_bf16 v[126:129], v[148:151], v[192:195], v[126:129]
	v_mfma_f32_16x16x32_bf16 v[122:125], v[168:171], v[192:195], v[122:125]
	v_mfma_f32_16x16x32_bf16 v[110:113], v[148:151], v[208:211], v[110:113]
	v_mfma_f32_16x16x32_bf16 v[106:109], v[168:171], v[208:211], v[106:109]
	v_mfma_f32_16x16x32_bf16 v[94:97], v[148:151], v[220:223], v[94:97]
	v_mfma_f32_16x16x32_bf16 v[90:93], v[168:171], v[220:223], v[90:93]
	v_mfma_f32_16x16x32_bf16 v[78:81], v[148:151], v[228:231], v[78:81]
	v_mfma_f32_16x16x32_bf16 v[74:77], v[168:171], v[228:231], v[74:77]
	s_setprio 0
	s_setprio 1
	v_mfma_f32_16x16x32_bf16 v[118:121], v[172:175], v[188:191], v[118:121]
	v_mfma_f32_16x16x32_bf16 v[114:117], v[180:183], v[188:191], v[114:117]
	v_mfma_f32_16x16x32_bf16 v[102:105], v[172:175], v[196:199], v[102:105]
	v_mfma_f32_16x16x32_bf16 v[98:101], v[180:183], v[196:199], v[98:101]
	v_mfma_f32_16x16x32_bf16 v[86:89], v[172:175], v[216:219], v[86:89]
	v_mfma_f32_16x16x32_bf16 v[82:85], v[180:183], v[216:219], v[82:85]
	v_mfma_f32_16x16x32_bf16 v[70:73], v[172:175], v[224:227], v[70:73]
	v_mfma_f32_16x16x32_bf16 v[66:69], v[180:183], v[224:227], v[66:69]
	v_mfma_f32_16x16x32_bf16 v[118:121], v[176:179], v[192:195], v[118:121]
	v_mfma_f32_16x16x32_bf16 v[114:117], v[184:187], v[192:195], v[114:117]
	v_mfma_f32_16x16x32_bf16 v[102:105], v[176:179], v[208:211], v[102:105]
	v_mfma_f32_16x16x32_bf16 v[98:101], v[184:187], v[208:211], v[98:101]
	v_mfma_f32_16x16x32_bf16 v[86:89], v[176:179], v[220:223], v[86:89]
	v_mfma_f32_16x16x32_bf16 v[82:85], v[184:187], v[220:223], v[82:85]
	v_mfma_f32_16x16x32_bf16 v[70:73], v[176:179], v[228:231], v[70:73]
	v_mfma_f32_16x16x32_bf16 v[66:69], v[184:187], v[228:231], v[66:69]
	s_setprio 0
	s_barrier
	s_add_i32 s75, s75, s51
	v_lshl_add_u64 v[146:147], s[44:45], 0, v[132:133]
	s_mov_b32 m0, s75
	ds_read_b128 v[188:191], v167 offset:16384
	ds_read_b128 v[192:195], v167 offset:17408
	ds_read_b128 v[196:199], v167 offset:18432
	ds_read_b128 v[208:211], v167 offset:19456
	ds_read_b128 v[216:219], v167 offset:20480
	ds_read_b128 v[220:223], v167 offset:21504
	ds_read_b128 v[224:227], v167 offset:22528
	ds_read_b128 v[228:231], v167 offset:23552
	global_load_lds_dwordx4 v[146:147], off
	s_add_i32 m0, s75, 0x2000
	s_add_u32 s76, s44, 0x40000
	v_lshl_add_u64 v[162:163], s[44:45], 0, v[136:137]
	s_addc_u32 s77, s45, 0
	s_add_i32 s43, s43, s51
	global_load_lds_dwordx4 v[162:163], off
	v_lshl_add_u64 v[200:201], s[76:77], 0, v[132:133]
	s_mov_b32 m0, s43
	v_lshl_add_u64 v[204:205], s[46:47], 0, v[134:135]
	global_load_lds_dwordx4 v[200:201], off
	v_lshl_add_u64 v[200:201], s[76:77], 0, v[136:137]
	s_add_i32 m0, s43, 0x2000
	s_nop 0
	global_load_lds_dwordx4 v[200:201], off
	v_lshl_add_u64 v[200:201], s[46:47], 0, v[130:131]
	s_mov_b32 m0, s59
	s_nop 0
	global_load_lds_dwordx4 v[200:201], off
	s_mov_b32 m0, s62
	s_nop 0
	global_load_lds_dwordx4 v[204:205], off
	s_waitcnt vmcnt(8)
	s_waitcnt lgkmcnt(0)
	s_barrier
; #define PG8_STAGE(bufoff, gbase, voff) do { _Pragma("unroll") for (int _i = 0; _i < 2; ++_i) \
;         __builtin_amdgcn_global_load_lds((const unsigned*)((const char*)(gbase) + (voff)[_i]), (PG8_LAS unsigned*)(lds + (bufoff) + ldsw + _i * 8192), 16, 0, 0); } while (0)
; #define PG8_LDA(dst, b, h) do { _Pragma("unroll") for (int m = 0; m < 4; ++m) _Pragma("unroll") for (int k = 0; k < 2; ++k) dst[m][k] = *(const PG8_LAS bf16x8*)(lds + PG8_SA(b, h) + aoff + m * 2048 + k * 1024); } while (0)
; #define PG8_LDB(dst, b, h) do { _Pragma("unroll") for (int n = 0; n < 2; ++n) _Pragma("unroll") for (int k = 0; k < 2; ++k) dst[n][k] = *(const PG8_LAS bf16x8*)(lds + PG8_SB(b, h) + boff + n * 2048 + k * 1024); } while (0)
; #define PG8_WAIT_V(n) asm volatile("s_waitcnt vmcnt(" #n ")" ::: "memory")
; #define PG8_WAIT_L(n) asm volatile("s_waitcnt lgkmcnt(" #n ")" ::: "memory")
; #define PG8_BAR __builtin_amdgcn_s_barrier()
; #define PG8_SCHED __builtin_amdgcn_sched_barrier(0)
; template <class Epi, bool ALIGN_EPI = true>
; __device__ __forceinline__ void gemm_phase(PG8_LAS unsigned char* lds, const Gemm g, const StaticOrder& S, const Epi& E) {
;     ...
;             PG8_WAIT_V(8); PG8_WAIT_L(0); PG8_BAR; PG8_MMA(1, 0, At, B0); PG8_MMA(1, 1, At, B1); PG8_BAR; PG8_SCHED;
;             PG8_LDB(B0, 1, 0); PG8_LDB(B1, 1, 1); PG8_SCHED; PG8_LDA(At, 1, 0); PG8_STAGE(PG8_SA(0, 1), a2 + hstepA, voffA);
;             PG8_WAIT_V(8); PG8_WAIT_L(0); PG8_BAR; PG8_MMA(0, 0, At, B0); PG8_MMA(0, 1, At, B1); PG8_BAR; PG8_SCHED;
	s_setprio 1
	s_waitcnt lgkmcnt(0)
	v_mfma_f32_16x16x32_bf16 v[62:65], v[142:145], v[188:191], v[62:65]
	v_mfma_f32_16x16x32_bf16 v[58:61], v[158:161], v[188:191], v[58:61]
	v_mfma_f32_16x16x32_bf16 v[46:49], v[142:145], v[196:199], v[46:49]
	v_mfma_f32_16x16x32_bf16 v[42:45], v[158:161], v[196:199], v[42:45]
	v_mfma_f32_16x16x32_bf16 v[28:31], v[142:145], v[216:219], v[28:31]
	v_mfma_f32_16x16x32_bf16 v[24:27], v[158:161], v[216:219], v[24:27]
	v_mfma_f32_16x16x32_bf16 v[12:15], v[142:145], v[224:227], v[12:15]
	v_mfma_f32_16x16x32_bf16 v[8:11], v[158:161], v[224:227], v[8:11]
	v_mfma_f32_16x16x32_bf16 v[62:65], v[148:151], v[192:195], v[62:65]
	v_mfma_f32_16x16x32_bf16 v[58:61], v[168:171], v[192:195], v[58:61]
	v_mfma_f32_16x16x32_bf16 v[46:49], v[148:151], v[208:211], v[46:49]
	v_mfma_f32_16x16x32_bf16 v[42:45], v[168:171], v[208:211], v[42:45]
	v_mfma_f32_16x16x32_bf16 v[28:31], v[148:151], v[220:223], v[28:31]
	v_mfma_f32_16x16x32_bf16 v[24:27], v[168:171], v[220:223], v[24:27]
	v_mfma_f32_16x16x32_bf16 v[12:15], v[148:151], v[228:231], v[12:15]
	v_mfma_f32_16x16x32_bf16 v[8:11], v[168:171], v[228:231], v[8:11]
	s_setprio 0
	s_setprio 1
	v_mfma_f32_16x16x32_bf16 v[54:57], v[172:175], v[188:191], v[54:57]
	v_mfma_f32_16x16x32_bf16 v[50:53], v[180:183], v[188:191], v[50:53]
	v_mfma_f32_16x16x32_bf16 v[38:41], v[172:175], v[196:199], v[38:41]
	v_mfma_f32_16x16x32_bf16 v[34:37], v[180:183], v[196:199], v[34:37]
	v_mfma_f32_16x16x32_bf16 v[20:23], v[172:175], v[216:219], v[20:23]
	v_mfma_f32_16x16x32_bf16 v[16:19], v[180:183], v[216:219], v[16:19]
	v_mfma_f32_16x16x32_bf16 v[4:7], v[172:175], v[224:227], v[4:7]
	v_mfma_f32_16x16x32_bf16 v[0:3], v[180:183], v[224:227], v[0:3]
	v_mfma_f32_16x16x32_bf16 v[54:57], v[176:179], v[192:195], v[54:57]
	v_mfma_f32_16x16x32_bf16 v[50:53], v[184:187], v[192:195], v[50:53]
	v_mfma_f32_16x16x32_bf16 v[38:41], v[176:179], v[208:211], v[38:41]
	v_mfma_f32_16x16x32_bf16 v[34:37], v[184:187], v[208:211], v[34:37]
	v_mfma_f32_16x16x32_bf16 v[20:23], v[176:179], v[220:223], v[20:23]
	v_mfma_f32_16x16x32_bf16 v[16:19], v[184:187], v[220:223], v[16:19]
	v_mfma_f32_16x16x32_bf16 v[4:7], v[176:179], v[228:231], v[4:7]
	v_mfma_f32_16x16x32_bf16 v[0:3], v[184:187], v[228:231], v[0:3]
	s_setprio 0
	s_barrier
	s_add_i32 s43, 0, 0x18000
	v_add_u32_e32 v32, s43, v165
	s_add_i32 s75, 0, 0x1c000
	ds_read_b128 v[142:145], v32
	ds_read_b128 v[148:151], v32 offset:1024
	ds_read_b128 v[158:161], v32 offset:2048
	ds_read_b128 v[168:171], v32 offset:3072
	v_add_u32_e32 v32, s75, v165
	ds_read_b128 v[172:175], v32
	ds_read_b128 v[176:179], v32 offset:1024
	ds_read_b128 v[180:183], v32 offset:2048
	ds_read_b128 v[184:187], v32 offset:3072
	s_add_u32 s46, s46, 0x40000
	s_addc_u32 s47, s47, 0
	s_mov_b32 m0, s63
	v_lshl_add_u64 v[206:207], s[46:47], 0, v[130:131]
	ds_read_b128 v[188:191], v167 offset:32768
	ds_read_b128 v[192:195], v167 offset:33792
	ds_read_b128 v[196:199], v167 offset:34816
	ds_read_b128 v[208:211], v167 offset:35840
	ds_read_b128 v[216:219], v167 offset:36864
	ds_read_b128 v[220:223], v167 offset:37888
	ds_read_b128 v[224:227], v167 offset:38912
	ds_read_b128 v[228:231], v167 offset:39936
	global_load_lds_dwordx4 v[206:207], off
	v_lshl_add_u64 v[206:207], s[46:47], 0, v[134:135]
	s_mov_b32 m0, s66
	s_nop 0
	global_load_lds_dwordx4 v[206:207], off
	s_waitcnt vmcnt(8)
	s_waitcnt lgkmcnt(0)
	s_barrier
	s_setprio 1
	s_waitcnt lgkmcnt(0)
	v_mfma_f32_16x16x32_bf16 v[126:129], v[142:145], v[188:191], v[126:129]
	v_mfma_f32_16x16x32_bf16 v[122:125], v[158:161], v[188:191], v[122:125]
	v_mfma_f32_16x16x32_bf16 v[110:113], v[142:145], v[196:199], v[110:113]
	v_mfma_f32_16x16x32_bf16 v[106:109], v[158:161], v[196:199], v[106:109]
	v_mfma_f32_16x16x32_bf16 v[94:97], v[142:145], v[216:219], v[94:97]
	v_mfma_f32_16x16x32_bf16 v[90:93], v[158:161], v[216:219], v[90:93]
	v_mfma_f32_16x16x32_bf16 v[78:81], v[142:145], v[224:227], v[78:81]
	v_mfma_f32_16x16x32_bf16 v[74:77], v[158:161], v[224:227], v[74:77]
	v_mfma_f32_16x16x32_bf16 v[126:129], v[148:151], v[192:195], v[126:129]
	v_mfma_f32_16x16x32_bf16 v[122:125], v[168:171], v[192:195], v[122:125]
	v_mfma_f32_16x16x32_bf16 v[110:113], v[148:151], v[208:211], v[110:113]
	v_mfma_f32_16x16x32_bf16 v[106:109], v[168:171], v[208:211], v[106:109]
	v_mfma_f32_16x16x32_bf16 v[94:97], v[148:151], v[220:223], v[94:97]
	v_mfma_f32_16x16x32_bf16 v[90:93], v[168:171], v[220:223], v[90:93]
	v_mfma_f32_16x16x32_bf16 v[78:81], v[148:151], v[228:231], v[78:81]
	v_mfma_f32_16x16x32_bf16 v[74:77], v[168:171], v[228:231], v[74:77]
	s_setprio 0
	s_setprio 1
	v_mfma_f32_16x16x32_bf16 v[118:121], v[172:175], v[188:191], v[118:121]
	v_mfma_f32_16x16x32_bf16 v[114:117], v[180:183], v[188:191], v[114:117]
	v_mfma_f32_16x16x32_bf16 v[102:105], v[172:175], v[196:199], v[102:105]
	v_mfma_f32_16x16x32_bf16 v[98:101], v[180:183], v[196:199], v[98:101]
	v_mfma_f32_16x16x32_bf16 v[86:89], v[172:175], v[216:219], v[86:89]
	v_mfma_f32_16x16x32_bf16 v[82:85], v[180:183], v[216:219], v[82:85]
	v_mfma_f32_16x16x32_bf16 v[70:73], v[172:175], v[224:227], v[70:73]
	v_mfma_f32_16x16x32_bf16 v[66:69], v[180:183], v[224:227], v[66:69]
	v_mfma_f32_16x16x32_bf16 v[118:121], v[176:179], v[192:195], v[118:121]
	v_mfma_f32_16x16x32_bf16 v[114:117], v[184:187], v[192:195], v[114:117]
	v_mfma_f32_16x16x32_bf16 v[102:105], v[176:179], v[208:211], v[102:105]
	v_mfma_f32_16x16x32_bf16 v[98:101], v[184:187], v[208:211], v[98:101]
	v_mfma_f32_16x16x32_bf16 v[86:89], v[176:179], v[220:223], v[86:89]
	v_mfma_f32_16x16x32_bf16 v[82:85], v[184:187], v[220:223], v[82:85]
	v_mfma_f32_16x16x32_bf16 v[70:73], v[176:179], v[228:231], v[70:73]
	v_mfma_f32_16x16x32_bf16 v[66:69], v[184:187], v[228:231], v[66:69]
	s_setprio 0
	s_barrier
; #define PG8_STAGE(bufoff, gbase, voff) do { _Pragma("unroll") for (int _i = 0; _i < 2; ++_i) \
;         __builtin_amdgcn_global_load_lds((const unsigned*)((const char*)(gbase) + (voff)[_i]), (PG8_LAS unsigned*)(lds + (bufoff) + ldsw + _i * 8192), 16, 0, 0); } while (0)
; #define PG8_LDA(dst, b, h) do { _Pragma("unroll") for (int m = 0; m < 4; ++m) _Pragma("unroll") for (int k = 0; k < 2; ++k) dst[m][k] = *(const PG8_LAS bf16x8*)(lds + PG8_SA(b, h) + aoff + m * 2048 + k * 1024); } while (0)
; #define PG8_WAIT_V(n) asm volatile("s_waitcnt vmcnt(" #n ")" ::: "memory")
; #define PG8_WAIT_L(n) asm volatile("s_waitcnt lgkmcnt(" #n ")" ::: "memory")
; #define PG8_BAR __builtin_amdgcn_s_barrier()
; #define PG8_SCHED __builtin_amdgcn_sched_barrier(0)
; template <class Epi, bool ALIGN_EPI = true>
; __device__ __forceinline__ void gemm_phase(PG8_LAS unsigned char* lds, const Gemm g, const StaticOrder& S, const Epi& E) {
;     ...
;             PG8_LDA(At, 1, 1); PG8_STAGE(PG8_SB(1, 0), b3, voffB); PG8_STAGE(PG8_SB(1, 1), b3 + hstepB, voffB); PG8_STAGE(PG8_SA(1, 0), a3, voffA);
;             PG8_WAIT_V(8); PG8_WAIT_L(0); PG8_BAR; PG8_MMA(1, 0, At, B0); PG8_MMA(1, 1, At, B1); PG8_BAR; PG8_SCHED;
	s_add_i32 s43, s43, s51
	v_lshl_add_u64 v[146:147], v[146:147], 0, s[60:61]
	s_mov_b32 m0, s43
	ds_read_b128 v[188:191], v167 offset:49152
	ds_read_b128 v[192:195], v167 offset:50176
	ds_read_b128 v[196:199], v167 offset:51200
	ds_read_b128 v[208:211], v167 offset:52224
	ds_read_b128 v[216:219], v167 offset:53248
	ds_read_b128 v[220:223], v167 offset:54272
	ds_read_b128 v[224:227], v167 offset:55296
	ds_read_b128 v[228:231], v167 offset:56320
	global_load_lds_dwordx4 v[146:147], off
	s_add_i32 m0, s43, 0x2000
	s_add_u32 s44, s44, 0x40080
	v_lshl_add_u64 v[146:147], v[162:163], 0, s[60:61]
	s_addc_u32 s45, s45, 0
	s_add_i32 s43, s75, s51
	global_load_lds_dwordx4 v[146:147], off
	v_lshl_add_u64 v[146:147], s[44:45], 0, v[132:133]
	s_mov_b32 m0, s43
	s_nop 0
	global_load_lds_dwordx4 v[146:147], off
	v_lshl_add_u64 v[146:147], s[44:45], 0, v[136:137]
	s_add_i32 m0, s43, 0x2000
	s_nop 0
	global_load_lds_dwordx4 v[146:147], off
	v_lshl_add_u64 v[146:147], v[200:201], 0, s[60:61]
	s_mov_b32 m0, s70
	s_nop 0
	global_load_lds_dwordx4 v[146:147], off
	v_lshl_add_u64 v[146:147], v[204:205], 0, s[60:61]
	s_mov_b32 m0, s71
	s_nop 0
	global_load_lds_dwordx4 v[146:147], off
	s_add_i32 s37, s37, 2
	s_add_u32 s6, s6, 0x100
	s_addc_u32 s7, s7, 0
	s_add_u32 s9, s9, 0x100
	s_addc_u32 s35, s35, 0
	s_add_u32 s43, s6, 0xfffc0080
	s_addc_u32 s44, s7, -1
	s_add_i32 s75, 0, 0x10000
	s_cmp_eq_u32 s37, 12
	s_cselect_b32 s47, s39, s44
	s_cselect_b32 s46, s38, s43
	v_add_u32_e32 v32, s75, v165
	s_cselect_b32 s45, s41, s35
	s_cselect_b32 s44, s40, s9
	s_add_i32 s43, 0, 0x14000
	s_cmp_gt_u32 s37, 13
	s_waitcnt vmcnt(8)
	s_waitcnt lgkmcnt(0)
	s_barrier
	s_setprio 1
	s_waitcnt lgkmcnt(0)
	v_mfma_f32_16x16x32_bf16 v[62:65], v[142:145], v[188:191], v[62:65]
	v_mfma_f32_16x16x32_bf16 v[58:61], v[158:161], v[188:191], v[58:61]
	v_mfma_f32_16x16x32_bf16 v[46:49], v[142:145], v[196:199], v[46:49]
	v_mfma_f32_16x16x32_bf16 v[42:45], v[158:161], v[196:199], v[42:45]
	v_mfma_f32_16x16x32_bf16 v[28:31], v[142:145], v[216:219], v[28:31]
	v_mfma_f32_16x16x32_bf16 v[24:27], v[158:161], v[216:219], v[24:27]
	v_mfma_f32_16x16x32_bf16 v[12:15], v[142:145], v[224:227], v[12:15]
	v_mfma_f32_16x16x32_bf16 v[8:11], v[158:161], v[224:227], v[8:11]
	v_mfma_f32_16x16x32_bf16 v[62:65], v[148:151], v[192:195], v[62:65]
	v_mfma_f32_16x16x32_bf16 v[58:61], v[168:171], v[192:195], v[58:61]
	v_mfma_f32_16x16x32_bf16 v[46:49], v[148:151], v[208:211], v[46:49]
	v_mfma_f32_16x16x32_bf16 v[42:45], v[168:171], v[208:211], v[42:45]
	v_mfma_f32_16x16x32_bf16 v[28:31], v[148:151], v[220:223], v[28:31]
	v_mfma_f32_16x16x32_bf16 v[24:27], v[168:171], v[220:223], v[24:27]
	v_mfma_f32_16x16x32_bf16 v[12:15], v[148:151], v[228:231], v[12:15]
	v_mfma_f32_16x16x32_bf16 v[8:11], v[168:171], v[228:231], v[8:11]
	s_setprio 0
	s_setprio 1
	v_mfma_f32_16x16x32_bf16 v[54:57], v[172:175], v[188:191], v[54:57]
	v_mfma_f32_16x16x32_bf16 v[50:53], v[180:183], v[188:191], v[50:53]
	v_mfma_f32_16x16x32_bf16 v[38:41], v[172:175], v[196:199], v[38:41]
	v_mfma_f32_16x16x32_bf16 v[34:37], v[180:183], v[196:199], v[34:37]
	v_mfma_f32_16x16x32_bf16 v[20:23], v[172:175], v[216:219], v[20:23]
	v_mfma_f32_16x16x32_bf16 v[16:19], v[180:183], v[216:219], v[16:19]
	v_mfma_f32_16x16x32_bf16 v[4:7], v[172:175], v[224:227], v[4:7]
	v_mfma_f32_16x16x32_bf16 v[0:3], v[180:183], v[224:227], v[0:3]
	v_mfma_f32_16x16x32_bf16 v[54:57], v[176:179], v[192:195], v[54:57]
	v_mfma_f32_16x16x32_bf16 v[50:53], v[184:187], v[192:195], v[50:53]
	v_mfma_f32_16x16x32_bf16 v[38:41], v[176:179], v[208:211], v[38:41]
	v_mfma_f32_16x16x32_bf16 v[34:37], v[184:187], v[208:211], v[34:37]
	v_mfma_f32_16x16x32_bf16 v[20:23], v[176:179], v[220:223], v[20:23]
	v_mfma_f32_16x16x32_bf16 v[16:19], v[184:187], v[220:223], v[16:19]
	v_mfma_f32_16x16x32_bf16 v[4:7], v[176:179], v[228:231], v[4:7]
	v_mfma_f32_16x16x32_bf16 v[0:3], v[184:187], v[228:231], v[0:3]
	s_setprio 0
	s_barrier
	s_cbranch_scc0 .Lrot_795
	s_and_b64 vcc, exec, s[26:27]
	s_cbranch_vccz .LBB0_798
	s_barrier

; #define PG8_STAGE(bufoff, gbase, voff) do { _Pragma("unroll") for (int _i = 0; _i < 2; ++_i) \
;         __builtin_amdgcn_global_load_lds((const unsigned*)((const char*)(gbase) + (voff)[_i]), (PG8_LAS unsigned*)(lds + (bufoff) + ldsw + _i * 8192), 16, 0, 0); } while (0)
; #define PG8_LDA(dst, b, h) do { _Pragma("unroll") for (int m = 0; m < 4; ++m) _Pragma("unroll") for (int k = 0; k < 2; ++k) dst[m][k] = *(const PG8_LAS bf16x8*)(lds + PG8_SA(b, h) + aoff + m * 2048 + k * 1024); } while (0)
; #define PG8_LDB(dst, b, h) do { _Pragma("unroll") for (int n = 0; n < 2; ++n) _Pragma("unroll") for (int k = 0; k < 2; ++k) dst[n][k] = *(const PG8_LAS bf16x8*)(lds + PG8_SB(b, h) + boff + n * 2048 + k * 1024); } while (0)
; #define PG8_WAIT_V(n) asm volatile("s_waitcnt vmcnt(" #n ")" ::: "memory")
; #define PG8_WAIT_L(n) asm volatile("s_waitcnt lgkmcnt(" #n ")" ::: "memory")
; #define PG8_BAR __builtin_amdgcn_s_barrier()
; #define PG8_SCHED __builtin_amdgcn_sched_barrier(0)
; template <class Epi, bool ALIGN_EPI = true>
; __device__ __forceinline__ void gemm_phase(PG8_LAS unsigned char* lds, const Gemm g, const StaticOrder& S, const Epi& E) {
;     ...
;             PG8_LDB(B0, 0, 0); PG8_LDB(B1, 0, 1); PG8_SCHED; PG8_LDA(At, 0, 0); PG8_STAGE(PG8_SA(1, 1), a1 + hstepA, voffA);
;             PG8_WAIT_V(8); PG8_WAIT_L(0); PG8_BAR; PG8_MMA(0, 0, At, B0); PG8_MMA(0, 1, At, B1); PG8_BAR; PG8_SCHED;
;             PG8_LDA(At, 0, 1); PG8_STAGE(PG8_SB(0, 0), b2, voffB); PG8_STAGE(PG8_SB(0, 1), b2 + hstepB, voffB); PG8_STAGE(PG8_SA(0, 0), a2, voffA);
;             PG8_WAIT_V(8); PG8_WAIT_L(0); PG8_BAR; PG8_MMA(1, 0, At, B0); PG8_MMA(1, 1, At, B1); PG8_BAR; PG8_SCHED;
.Lrot_1004:
	ds_read_b128 v[130:133], v32
	ds_read_b128 v[134:137], v32 offset:1024
	ds_read_b128 v[164:167], v32 offset:2048
	ds_read_b128 v[168:171], v32 offset:3072
	v_add_u32_e32 v32, s52, v143
	ds_read_b128 v[172:175], v32
	ds_read_b128 v[176:179], v32 offset:1024
	ds_read_b128 v[180:183], v32 offset:2048
	ds_read_b128 v[184:187], v32 offset:3072
	v_lshl_add_u64 v[146:147], s[20:21], 0, v[158:159]
	s_add_i32 m0, s35, 0xc000
	ds_read_b128 v[188:191], v163
	ds_read_b128 v[192:195], v163 offset:1024
	ds_read_b128 v[196:199], v163 offset:2048
	ds_read_b128 v[216:219], v163 offset:3072
	ds_read_b128 v[220:223], v163 offset:4096
	ds_read_b128 v[224:227], v163 offset:5120
	ds_read_b128 v[228:231], v163 offset:6144
	ds_read_b128 v[232:235], v163 offset:7168
	global_load_lds_dwordx4 v[146:147], off
	v_lshl_add_u64 v[146:147], s[20:21], 0, v[160:161]
	s_add_i32 m0, s35, 0xe000
	s_nop 0
	global_load_lds_dwordx4 v[146:147], off
	s_waitcnt vmcnt(8)
	s_waitcnt lgkmcnt(0)
	s_barrier
	s_setprio 1
	s_waitcnt lgkmcnt(0)
	v_mfma_f32_16x16x32_bf16 v[126:129], v[188:191], v[130:133], v[126:129]
	v_mfma_f32_16x16x32_bf16 v[122:125], v[188:191], v[164:167], v[122:125]
	v_mfma_f32_16x16x32_bf16 v[110:113], v[196:199], v[130:133], v[110:113]
	v_mfma_f32_16x16x32_bf16 v[106:109], v[196:199], v[164:167], v[106:109]
	v_mfma_f32_16x16x32_bf16 v[94:97], v[220:223], v[130:133], v[94:97]
	v_mfma_f32_16x16x32_bf16 v[90:93], v[220:223], v[164:167], v[90:93]
	v_mfma_f32_16x16x32_bf16 v[78:81], v[228:231], v[130:133], v[78:81]
	v_mfma_f32_16x16x32_bf16 v[74:77], v[228:231], v[164:167], v[74:77]
	v_mfma_f32_16x16x32_bf16 v[126:129], v[192:195], v[134:137], v[126:129]
	v_mfma_f32_16x16x32_bf16 v[122:125], v[192:195], v[168:171], v[122:125]
	v_mfma_f32_16x16x32_bf16 v[110:113], v[216:219], v[134:137], v[110:113]
	v_mfma_f32_16x16x32_bf16 v[106:109], v[216:219], v[168:171], v[106:109]
	v_mfma_f32_16x16x32_bf16 v[94:97], v[224:227], v[134:137], v[94:97]
	v_mfma_f32_16x16x32_bf16 v[90:93], v[224:227], v[168:171], v[90:93]
	v_mfma_f32_16x16x32_bf16 v[78:81], v[232:235], v[134:137], v[78:81]
	v_mfma_f32_16x16x32_bf16 v[74:77], v[232:235], v[168:171], v[74:77]
	s_setprio 0
	s_setprio 1
	v_mfma_f32_16x16x32_bf16 v[118:121], v[188:191], v[172:175], v[118:121]
	v_mfma_f32_16x16x32_bf16 v[114:117], v[188:191], v[180:183], v[114:117]
	v_mfma_f32_16x16x32_bf16 v[102:105], v[196:199], v[172:175], v[102:105]
	v_mfma_f32_16x16x32_bf16 v[98:101], v[196:199], v[180:183], v[98:101]
	v_mfma_f32_16x16x32_bf16 v[86:89], v[220:223], v[172:175], v[86:89]
	v_mfma_f32_16x16x32_bf16 v[82:85], v[220:223], v[180:183], v[82:85]
	v_mfma_f32_16x16x32_bf16 v[70:73], v[228:231], v[172:175], v[70:73]
	v_mfma_f32_16x16x32_bf16 v[66:69], v[228:231], v[180:183], v[66:69]
	v_mfma_f32_16x16x32_bf16 v[118:121], v[192:195], v[176:179], v[118:121]
	v_mfma_f32_16x16x32_bf16 v[114:117], v[192:195], v[184:187], v[114:117]
	v_mfma_f32_16x16x32_bf16 v[102:105], v[216:219], v[176:179], v[102:105]
	v_mfma_f32_16x16x32_bf16 v[98:101], v[216:219], v[184:187], v[98:101]
	v_mfma_f32_16x16x32_bf16 v[86:89], v[224:227], v[176:179], v[86:89]
	v_mfma_f32_16x16x32_bf16 v[82:85], v[224:227], v[184:187], v[82:85]
	v_mfma_f32_16x16x32_bf16 v[70:73], v[232:235], v[176:179], v[70:73]
	v_mfma_f32_16x16x32_bf16 v[66:69], v[232:235], v[184:187], v[66:69]
	s_setprio 0
	s_barrier
	s_add_i32 s50, s50, s34
	v_lshl_add_u64 v[146:147], s[22:23], 0, v[138:139]
	s_mov_b32 m0, s50
	ds_read_b128 v[188:191], v163 offset:16384
	ds_read_b128 v[192:195], v163 offset:17408
	ds_read_b128 v[196:199], v163 offset:18432
	ds_read_b128 v[216:219], v163 offset:19456
	ds_read_b128 v[220:223], v163 offset:20480
	ds_read_b128 v[224:227], v163 offset:21504
	ds_read_b128 v[228:231], v163 offset:22528
	ds_read_b128 v[232:235], v163 offset:23552
	global_load_lds_dwordx4 v[146:147], off
	s_add_i32 m0, s50, 0x2000
	s_add_u32 s50, s22, 0x40000
	v_lshl_add_u64 v[148:149], s[22:23], 0, v[140:141]
	s_addc_u32 s51, s23, 0
	s_add_i32 s52, s52, s34
	global_load_lds_dwordx4 v[148:149], off
	v_lshl_add_u64 v[150:151], s[50:51], 0, v[138:139]
	s_mov_b32 m0, s52
	v_lshl_add_u64 v[200:201], s[24:25], 0, v[140:141]
	global_load_lds_dwordx4 v[150:151], off
	v_lshl_add_u64 v[150:151], s[50:51], 0, v[140:141]
	s_add_i32 m0, s52, 0x2000
	s_nop 0
	global_load_lds_dwordx4 v[150:151], off
	v_lshl_add_u64 v[150:151], s[24:25], 0, v[138:139]
	s_mov_b32 m0, s35
	s_nop 0
	global_load_lds_dwordx4 v[150:151], off
	s_mov_b32 m0, s36
	s_nop 0
	global_load_lds_dwordx4 v[200:201], off
	s_waitcnt vmcnt(8)
	s_waitcnt lgkmcnt(0)
	s_barrier
; #define PG8_STAGE(bufoff, gbase, voff) do { _Pragma("unroll") for (int _i = 0; _i < 2; ++_i) \
;         __builtin_amdgcn_global_load_lds((const unsigned*)((const char*)(gbase) + (voff)[_i]), (PG8_LAS unsigned*)(lds + (bufoff) + ldsw + _i * 8192), 16, 0, 0); } while (0)
; #define PG8_LDA(dst, b, h) do { _Pragma("unroll") for (int m = 0; m < 4; ++m) _Pragma("unroll") for (int k = 0; k < 2; ++k) dst[m][k] = *(const PG8_LAS bf16x8*)(lds + PG8_SA(b, h) + aoff + m * 2048 + k * 1024); } while (0)
; #define PG8_LDB(dst, b, h) do { _Pragma("unroll") for (int n = 0; n < 2; ++n) _Pragma("unroll") for (int k = 0; k < 2; ++k) dst[n][k] = *(const PG8_LAS bf16x8*)(lds + PG8_SB(b, h) + boff + n * 2048 + k * 1024); } while (0)
; #define PG8_WAIT_V(n) asm volatile("s_waitcnt vmcnt(" #n ")" ::: "memory")
; #define PG8_WAIT_L(n) asm volatile("s_waitcnt lgkmcnt(" #n ")" ::: "memory")
; #define PG8_BAR __builtin_amdgcn_s_barrier()
; #define PG8_SCHED __builtin_amdgcn_sched_barrier(0)
; template <class Epi, bool ALIGN_EPI = true>
; __device__ __forceinline__ void gemm_phase(PG8_LAS unsigned char* lds, const Gemm g, const StaticOrder& S, const Epi& E) {
;     ...
;             PG8_WAIT_V(8); PG8_WAIT_L(0); PG8_BAR; PG8_MMA(1, 0, At, B0); PG8_MMA(1, 1, At, B1); PG8_BAR; PG8_SCHED;
;             PG8_LDB(B0, 1, 0); PG8_LDB(B1, 1, 1); PG8_SCHED; PG8_LDA(At, 1, 0); PG8_STAGE(PG8_SA(0, 1), a2 + hstepA, voffA);
;             PG8_WAIT_V(8); PG8_WAIT_L(0); PG8_BAR; PG8_MMA(0, 0, At, B0); PG8_MMA(0, 1, At, B1); PG8_BAR; PG8_SCHED;
	s_setprio 1
	s_waitcnt lgkmcnt(0)
	v_mfma_f32_16x16x32_bf16 v[62:65], v[188:191], v[130:133], v[62:65]
	v_mfma_f32_16x16x32_bf16 v[58:61], v[188:191], v[164:167], v[58:61]
	v_mfma_f32_16x16x32_bf16 v[46:49], v[196:199], v[130:133], v[46:49]
	v_mfma_f32_16x16x32_bf16 v[42:45], v[196:199], v[164:167], v[42:45]
	v_mfma_f32_16x16x32_bf16 v[28:31], v[220:223], v[130:133], v[28:31]
	v_mfma_f32_16x16x32_bf16 v[24:27], v[220:223], v[164:167], v[24:27]
	v_mfma_f32_16x16x32_bf16 v[12:15], v[228:231], v[130:133], v[12:15]
	v_mfma_f32_16x16x32_bf16 v[8:11], v[228:231], v[164:167], v[8:11]
	v_mfma_f32_16x16x32_bf16 v[62:65], v[192:195], v[134:137], v[62:65]
	v_mfma_f32_16x16x32_bf16 v[58:61], v[192:195], v[168:171], v[58:61]
	v_mfma_f32_16x16x32_bf16 v[46:49], v[216:219], v[134:137], v[46:49]
	v_mfma_f32_16x16x32_bf16 v[42:45], v[216:219], v[168:171], v[42:45]
	v_mfma_f32_16x16x32_bf16 v[28:31], v[224:227], v[134:137], v[28:31]
	v_mfma_f32_16x16x32_bf16 v[24:27], v[224:227], v[168:171], v[24:27]
	v_mfma_f32_16x16x32_bf16 v[12:15], v[232:235], v[134:137], v[12:15]
	v_mfma_f32_16x16x32_bf16 v[8:11], v[232:235], v[168:171], v[8:11]
	s_setprio 0
	s_setprio 1
	v_mfma_f32_16x16x32_bf16 v[54:57], v[188:191], v[172:175], v[54:57]
	v_mfma_f32_16x16x32_bf16 v[50:53], v[188:191], v[180:183], v[50:53]
	v_mfma_f32_16x16x32_bf16 v[38:41], v[196:199], v[172:175], v[38:41]
	v_mfma_f32_16x16x32_bf16 v[34:37], v[196:199], v[180:183], v[34:37]
	v_mfma_f32_16x16x32_bf16 v[20:23], v[220:223], v[172:175], v[20:23]
	v_mfma_f32_16x16x32_bf16 v[16:19], v[220:223], v[180:183], v[16:19]
	v_mfma_f32_16x16x32_bf16 v[4:7], v[228:231], v[172:175], v[4:7]
	v_mfma_f32_16x16x32_bf16 v[0:3], v[228:231], v[180:183], v[0:3]
	v_mfma_f32_16x16x32_bf16 v[54:57], v[192:195], v[176:179], v[54:57]
	v_mfma_f32_16x16x32_bf16 v[50:53], v[192:195], v[184:187], v[50:53]
	v_mfma_f32_16x16x32_bf16 v[38:41], v[216:219], v[176:179], v[38:41]
	v_mfma_f32_16x16x32_bf16 v[34:37], v[216:219], v[184:187], v[34:37]
	v_mfma_f32_16x16x32_bf16 v[20:23], v[224:227], v[176:179], v[20:23]
	v_mfma_f32_16x16x32_bf16 v[16:19], v[224:227], v[184:187], v[16:19]
	v_mfma_f32_16x16x32_bf16 v[4:7], v[232:235], v[176:179], v[4:7]
	v_mfma_f32_16x16x32_bf16 v[0:3], v[232:235], v[184:187], v[0:3]
	s_setprio 0
	s_barrier
	s_add_i32 s50, 0, 0x18000
	v_add_u32_e32 v32, s50, v143
	s_add_i32 s51, 0, 0x1c000
	ds_read_b128 v[130:133], v32
	ds_read_b128 v[134:137], v32 offset:1024
	ds_read_b128 v[164:167], v32 offset:2048
	ds_read_b128 v[168:171], v32 offset:3072
	v_add_u32_e32 v32, s51, v143
	ds_read_b128 v[172:175], v32
	ds_read_b128 v[176:179], v32 offset:1024
	ds_read_b128 v[180:183], v32 offset:2048
	ds_read_b128 v[184:187], v32 offset:3072
	s_add_u32 s24, s24, 0x40000
	s_addc_u32 s25, s25, 0
	s_mov_b32 m0, s37
	v_lshl_add_u64 v[204:205], s[24:25], 0, v[138:139]
	ds_read_b128 v[188:191], v163 offset:32768
	ds_read_b128 v[192:195], v163 offset:33792
	ds_read_b128 v[196:199], v163 offset:34816
	ds_read_b128 v[216:219], v163 offset:35840
	ds_read_b128 v[220:223], v163 offset:36864
	ds_read_b128 v[224:227], v163 offset:37888
	ds_read_b128 v[228:231], v163 offset:38912
	ds_read_b128 v[232:235], v163 offset:39936
	global_load_lds_dwordx4 v[204:205], off
	v_lshl_add_u64 v[204:205], s[24:25], 0, v[140:141]
	s_mov_b32 m0, s38
	s_nop 0
	global_load_lds_dwordx4 v[204:205], off
	s_waitcnt vmcnt(8)
	s_waitcnt lgkmcnt(0)
	s_barrier
	s_setprio 1
	s_waitcnt lgkmcnt(0)
	v_mfma_f32_16x16x32_bf16 v[126:129], v[188:191], v[130:133], v[126:129]
	v_mfma_f32_16x16x32_bf16 v[122:125], v[188:191], v[164:167], v[122:125]
	v_mfma_f32_16x16x32_bf16 v[110:113], v[196:199], v[130:133], v[110:113]
	v_mfma_f32_16x16x32_bf16 v[106:109], v[196:199], v[164:167], v[106:109]
	v_mfma_f32_16x16x32_bf16 v[94:97], v[220:223], v[130:133], v[94:97]
	v_mfma_f32_16x16x32_bf16 v[90:93], v[220:223], v[164:167], v[90:93]
	v_mfma_f32_16x16x32_bf16 v[78:81], v[228:231], v[130:133], v[78:81]
	v_mfma_f32_16x16x32_bf16 v[74:77], v[228:231], v[164:167], v[74:77]
	v_mfma_f32_16x16x32_bf16 v[126:129], v[192:195], v[134:137], v[126:129]
	v_mfma_f32_16x16x32_bf16 v[122:125], v[192:195], v[168:171], v[122:125]
	v_mfma_f32_16x16x32_bf16 v[110:113], v[216:219], v[134:137], v[110:113]
	v_mfma_f32_16x16x32_bf16 v[106:109], v[216:219], v[168:171], v[106:109]
	v_mfma_f32_16x16x32_bf16 v[94:97], v[224:227], v[134:137], v[94:97]
	v_mfma_f32_16x16x32_bf16 v[90:93], v[224:227], v[168:171], v[90:93]
	v_mfma_f32_16x16x32_bf16 v[78:81], v[232:235], v[134:137], v[78:81]
	v_mfma_f32_16x16x32_bf16 v[74:77], v[232:235], v[168:171], v[74:77]
	s_setprio 0
	s_setprio 1
	v_mfma_f32_16x16x32_bf16 v[118:121], v[188:191], v[172:175], v[118:121]
	v_mfma_f32_16x16x32_bf16 v[114:117], v[188:191], v[180:183], v[114:117]
	v_mfma_f32_16x16x32_bf16 v[102:105], v[196:199], v[172:175], v[102:105]
	v_mfma_f32_16x16x32_bf16 v[98:101], v[196:199], v[180:183], v[98:101]
	v_mfma_f32_16x16x32_bf16 v[86:89], v[220:223], v[172:175], v[86:89]
	v_mfma_f32_16x16x32_bf16 v[82:85], v[220:223], v[180:183], v[82:85]
	v_mfma_f32_16x16x32_bf16 v[70:73], v[228:231], v[172:175], v[70:73]
	v_mfma_f32_16x16x32_bf16 v[66:69], v[228:231], v[180:183], v[66:69]
	v_mfma_f32_16x16x32_bf16 v[118:121], v[192:195], v[176:179], v[118:121]
	v_mfma_f32_16x16x32_bf16 v[114:117], v[192:195], v[184:187], v[114:117]
	v_mfma_f32_16x16x32_bf16 v[102:105], v[216:219], v[176:179], v[102:105]
	v_mfma_f32_16x16x32_bf16 v[98:101], v[216:219], v[184:187], v[98:101]
	v_mfma_f32_16x16x32_bf16 v[86:89], v[224:227], v[176:179], v[86:89]
	v_mfma_f32_16x16x32_bf16 v[82:85], v[224:227], v[184:187], v[82:85]
	v_mfma_f32_16x16x32_bf16 v[70:73], v[232:235], v[176:179], v[70:73]
	v_mfma_f32_16x16x32_bf16 v[66:69], v[232:235], v[184:187], v[66:69]
	s_setprio 0
	s_barrier
; #define PG8_STAGE(bufoff, gbase, voff) do { _Pragma("unroll") for (int _i = 0; _i < 2; ++_i) \
;         __builtin_amdgcn_global_load_lds((const unsigned*)((const char*)(gbase) + (voff)[_i]), (PG8_LAS unsigned*)(lds + (bufoff) + ldsw + _i * 8192), 16, 0, 0); } while (0)
; #define PG8_LDA(dst, b, h) do { _Pragma("unroll") for (int m = 0; m < 4; ++m) _Pragma("unroll") for (int k = 0; k < 2; ++k) dst[m][k] = *(const PG8_LAS bf16x8*)(lds + PG8_SA(b, h) + aoff + m * 2048 + k * 1024); } while (0)
; #define PG8_WAIT_V(n) asm volatile("s_waitcnt vmcnt(" #n ")" ::: "memory")
; #define PG8_WAIT_L(n) asm volatile("s_waitcnt lgkmcnt(" #n ")" ::: "memory")
; #define PG8_BAR __builtin_amdgcn_s_barrier()
; #define PG8_SCHED __builtin_amdgcn_sched_barrier(0)
; template <class Epi, bool ALIGN_EPI = true>
; __device__ __forceinline__ void gemm_phase(PG8_LAS unsigned char* lds, const Gemm g, const StaticOrder& S, const Epi& E) {
;     ...
;         for (int t = 0; t < nt; t += 2) {
;             const bool last = (t == nt - 2);
;             const char* a1 = cA + (size_t)(t + 1) * kstep;
;             const char* a2 = last ? nA : cA + (size_t)(t + 2) * kstep; const char* b2 = last ? nB : cB + (size_t)(t + 2) * kstep;
;     ...
;             PG8_LDA(At, 1, 1); PG8_STAGE(PG8_SB(1, 0), b3, voffB); PG8_STAGE(PG8_SB(1, 1), b3 + hstepB, voffB); PG8_STAGE(PG8_SA(1, 0), a3, voffA);
;             PG8_WAIT_V(8); PG8_WAIT_L(0); PG8_BAR; PG8_MMA(1, 0, At, B0); PG8_MMA(1, 1, At, B1); PG8_BAR; PG8_SCHED;
	s_add_i32 s24, s50, s34
	v_lshl_add_u64 v[146:147], v[146:147], 0, s[60:61]
	s_mov_b32 m0, s24
	ds_read_b128 v[188:191], v163 offset:49152
	ds_read_b128 v[192:195], v163 offset:50176
	ds_read_b128 v[196:199], v163 offset:51200
	ds_read_b128 v[216:219], v163 offset:52224
	ds_read_b128 v[220:223], v163 offset:53248
	ds_read_b128 v[224:227], v163 offset:54272
	ds_read_b128 v[228:231], v163 offset:55296
	ds_read_b128 v[232:235], v163 offset:56320
	global_load_lds_dwordx4 v[146:147], off
	s_add_i32 m0, s24, 0x2000
	s_add_u32 s22, s22, 0x40080
	v_lshl_add_u64 v[146:147], v[148:149], 0, s[60:61]
	s_addc_u32 s23, s23, 0
	s_add_i32 s24, s51, s34
	global_load_lds_dwordx4 v[146:147], off
	v_lshl_add_u64 v[146:147], s[22:23], 0, v[138:139]
	s_mov_b32 m0, s24
	s_nop 0
	global_load_lds_dwordx4 v[146:147], off
	v_lshl_add_u64 v[146:147], s[22:23], 0, v[140:141]
	s_add_i32 m0, s24, 0x2000
	s_nop 0
	global_load_lds_dwordx4 v[146:147], off
	v_lshl_add_u64 v[146:147], v[150:151], 0, s[60:61]
	s_mov_b32 m0, s42
	s_nop 0
	global_load_lds_dwordx4 v[146:147], off
	v_lshl_add_u64 v[146:147], v[200:201], 0, s[60:61]
	s_mov_b32 m0, s43
	s_nop 0
	global_load_lds_dwordx4 v[146:147], off
	s_add_i32 s49, s49, 2
	s_add_u32 s20, s20, 0x100
	s_addc_u32 s21, s21, 0
	s_add_u32 s47, s47, 0x100
	s_addc_u32 s48, s48, 0
	s_add_u32 s22, s20, 0xfffc0080
	s_addc_u32 s23, s21, -1
	s_add_i32 s50, 0, 0x10000
	s_cmp_eq_u32 s49, 12
	s_cselect_b32 s25, s11, s23
	s_cselect_b32 s24, s17, s22
	v_add_u32_e32 v32, s50, v143
	s_cselect_b32 s23, s9, s48
	s_cselect_b32 s22, s19, s47
	s_add_i32 s52, 0, 0x14000
	s_cmp_gt_u32 s49, 13
	s_waitcnt vmcnt(8)
	s_waitcnt lgkmcnt(0)
	s_barrier
	s_setprio 1
	s_waitcnt lgkmcnt(0)
	v_mfma_f32_16x16x32_bf16 v[62:65], v[188:191], v[130:133], v[62:65]
	v_mfma_f32_16x16x32_bf16 v[58:61], v[188:191], v[164:167], v[58:61]
	v_mfma_f32_16x16x32_bf16 v[46:49], v[196:199], v[130:133], v[46:49]
	v_mfma_f32_16x16x32_bf16 v[42:45], v[196:199], v[164:167], v[42:45]
	v_mfma_f32_16x16x32_bf16 v[28:31], v[220:223], v[130:133], v[28:31]
	v_mfma_f32_16x16x32_bf16 v[24:27], v[220:223], v[164:167], v[24:27]
	v_mfma_f32_16x16x32_bf16 v[12:15], v[228:231], v[130:133], v[12:15]
	v_mfma_f32_16x16x32_bf16 v[8:11], v[228:231], v[164:167], v[8:11]
	v_mfma_f32_16x16x32_bf16 v[62:65], v[192:195], v[134:137], v[62:65]
	v_mfma_f32_16x16x32_bf16 v[58:61], v[192:195], v[168:171], v[58:61]
	v_mfma_f32_16x16x32_bf16 v[46:49], v[216:219], v[134:137], v[46:49]
	v_mfma_f32_16x16x32_bf16 v[42:45], v[216:219], v[168:171], v[42:45]
	v_mfma_f32_16x16x32_bf16 v[28:31], v[224:227], v[134:137], v[28:31]
	v_mfma_f32_16x16x32_bf16 v[24:27], v[224:227], v[168:171], v[24:27]
	v_mfma_f32_16x16x32_bf16 v[12:15], v[232:235], v[134:137], v[12:15]
	v_mfma_f32_16x16x32_bf16 v[8:11], v[232:235], v[168:171], v[8:11]
	s_setprio 0
	s_setprio 1
	v_mfma_f32_16x16x32_bf16 v[54:57], v[188:191], v[172:175], v[54:57]
	v_mfma_f32_16x16x32_bf16 v[50:53], v[188:191], v[180:183], v[50:53]
	v_mfma_f32_16x16x32_bf16 v[38:41], v[196:199], v[172:175], v[38:41]
	v_mfma_f32_16x16x32_bf16 v[34:37], v[196:199], v[180:183], v[34:37]
	v_mfma_f32_16x16x32_bf16 v[20:23], v[220:223], v[172:175], v[20:23]
	v_mfma_f32_16x16x32_bf16 v[16:19], v[220:223], v[180:183], v[16:19]
	v_mfma_f32_16x16x32_bf16 v[4:7], v[228:231], v[172:175], v[4:7]
	v_mfma_f32_16x16x32_bf16 v[0:3], v[228:231], v[180:183], v[0:3]
	v_mfma_f32_16x16x32_bf16 v[54:57], v[192:195], v[176:179], v[54:57]
	v_mfma_f32_16x16x32_bf16 v[50:53], v[192:195], v[184:187], v[50:53]
	v_mfma_f32_16x16x32_bf16 v[38:41], v[216:219], v[176:179], v[38:41]
	v_mfma_f32_16x16x32_bf16 v[34:37], v[216:219], v[184:187], v[34:37]
	v_mfma_f32_16x16x32_bf16 v[20:23], v[224:227], v[176:179], v[20:23]
	v_mfma_f32_16x16x32_bf16 v[16:19], v[224:227], v[184:187], v[16:19]
	v_mfma_f32_16x16x32_bf16 v[4:7], v[232:235], v[176:179], v[4:7]
	v_mfma_f32_16x16x32_bf16 v[0:3], v[232:235], v[184:187], v[0:3]
	s_setprio 0
	s_barrier
	s_cbranch_scc0 .Lrot_1004
	s_and_b64 vcc, exec, s[6:7]
	s_cbranch_vccz .LBB0_1007
	s_barrier

; #define PG8_STAGE(bufoff, gbase, voff) do { _Pragma("unroll") for (int _i = 0; _i < 2; ++_i) \
;         __builtin_amdgcn_global_load_lds((const unsigned*)((const char*)(gbase) + (voff)[_i]), (PG8_LAS unsigned*)(lds + (bufoff) + ldsw + _i * 8192), 16, 0, 0); } while (0)
; #define PG8_LDA(dst, b, h) do { _Pragma("unroll") for (int m = 0; m < 4; ++m) _Pragma("unroll") for (int k = 0; k < 2; ++k) dst[m][k] = *(const PG8_LAS bf16x8*)(lds + PG8_SA(b, h) + aoff + m * 2048 + k * 1024); } while (0)
; #define PG8_LDB(dst, b, h) do { _Pragma("unroll") for (int n = 0; n < 2; ++n) _Pragma("unroll") for (int k = 0; k < 2; ++k) dst[n][k] = *(const PG8_LAS bf16x8*)(lds + PG8_SB(b, h) + boff + n * 2048 + k * 1024); } while (0)
; #define PG8_WAIT_V(n) asm volatile("s_waitcnt vmcnt(" #n ")" ::: "memory")
; #define PG8_WAIT_L(n) asm volatile("s_waitcnt lgkmcnt(" #n ")" ::: "memory")
; #define PG8_BAR __builtin_amdgcn_s_barrier()
; #define PG8_SCHED __builtin_amdgcn_sched_barrier(0)
; template <class Epi, bool ALIGN_EPI = true>
; __device__ __forceinline__ void gemm_phase(PG8_LAS unsigned char* lds, const Gemm g, const StaticOrder& S, const Epi& E) {
;     ...
;             PG8_LDB(B0, 0, 0); PG8_LDB(B1, 0, 1); PG8_SCHED; PG8_LDA(At, 0, 0); PG8_STAGE(PG8_SA(1, 1), a1 + hstepA, voffA);
;             PG8_WAIT_V(8); PG8_WAIT_L(0); PG8_BAR; PG8_MMA(0, 0, At, B0); PG8_MMA(0, 1, At, B1); PG8_BAR; PG8_SCHED;
;             PG8_LDA(At, 0, 1); PG8_STAGE(PG8_SB(0, 0), b2, voffB); PG8_STAGE(PG8_SB(0, 1), b2 + hstepB, voffB); PG8_STAGE(PG8_SA(0, 0), a2, voffA);
.Lrot_1829:
	ds_read_b128 v[142:145], v32
	ds_read_b128 v[148:151], v32 offset:1024
	ds_read_b128 v[158:161], v32 offset:2048
	ds_read_b128 v[168:171], v32 offset:3072
	v_add_u32_e32 v32, s43, v165
	ds_read_b128 v[172:175], v32
	ds_read_b128 v[176:179], v32 offset:1024
	ds_read_b128 v[180:183], v32 offset:2048
	ds_read_b128 v[184:187], v32 offset:3072
	v_lshl_add_u64 v[146:147], s[6:7], 0, v[138:139]
	s_add_i32 m0, s59, 0xc000
	ds_read_b128 v[188:191], v167
	ds_read_b128 v[192:195], v167 offset:1024
	ds_read_b128 v[196:199], v167 offset:2048
	ds_read_b128 v[208:211], v167 offset:3072
	ds_read_b128 v[216:219], v167 offset:4096
	ds_read_b128 v[220:223], v167 offset:5120
	ds_read_b128 v[224:227], v167 offset:6144
	ds_read_b128 v[228:231], v167 offset:7168
	global_load_lds_dwordx4 v[146:147], off
	v_lshl_add_u64 v[146:147], s[6:7], 0, v[140:141]
	s_add_i32 m0, s59, 0xe000
	s_nop 0
	global_load_lds_dwordx4 v[146:147], off
	s_waitcnt vmcnt(8)
	s_waitcnt lgkmcnt(0)
	s_barrier
	s_setprio 1
	s_waitcnt lgkmcnt(0)
	v_mfma_f32_16x16x32_bf16 v[126:129], v[142:145], v[188:191], v[126:129]
	v_mfma_f32_16x16x32_bf16 v[122:125], v[158:161], v[188:191], v[122:125]
	v_mfma_f32_16x16x32_bf16 v[110:113], v[142:145], v[196:199], v[110:113]
	v_mfma_f32_16x16x32_bf16 v[106:109], v[158:161], v[196:199], v[106:109]
	v_mfma_f32_16x16x32_bf16 v[94:97], v[142:145], v[216:219], v[94:97]
	v_mfma_f32_16x16x32_bf16 v[90:93], v[158:161], v[216:219], v[90:93]
	v_mfma_f32_16x16x32_bf16 v[78:81], v[142:145], v[224:227], v[78:81]
	v_mfma_f32_16x16x32_bf16 v[74:77], v[158:161], v[224:227], v[74:77]
	v_mfma_f32_16x16x32_bf16 v[126:129], v[148:151], v[192:195], v[126:129]
	v_mfma_f32_16x16x32_bf16 v[122:125], v[168:171], v[192:195], v[122:125]
	v_mfma_f32_16x16x32_bf16 v[110:113], v[148:151], v[208:211], v[110:113]
	v_mfma_f32_16x16x32_bf16 v[106:109], v[168:171], v[208:211], v[106:109]
	v_mfma_f32_16x16x32_bf16 v[94:97], v[148:151], v[220:223], v[94:97]
	v_mfma_f32_16x16x32_bf16 v[90:93], v[168:171], v[220:223], v[90:93]
	v_mfma_f32_16x16x32_bf16 v[78:81], v[148:151], v[228:231], v[78:81]
	v_mfma_f32_16x16x32_bf16 v[74:77], v[168:171], v[228:231], v[74:77]
	s_setprio 0
	s_setprio 1
	v_mfma_f32_16x16x32_bf16 v[118:121], v[172:175], v[188:191], v[118:121]
	v_mfma_f32_16x16x32_bf16 v[114:117], v[180:183], v[188:191], v[114:117]
	v_mfma_f32_16x16x32_bf16 v[102:105], v[172:175], v[196:199], v[102:105]
	v_mfma_f32_16x16x32_bf16 v[98:101], v[180:183], v[196:199], v[98:101]
	v_mfma_f32_16x16x32_bf16 v[86:89], v[172:175], v[216:219], v[86:89]
	v_mfma_f32_16x16x32_bf16 v[82:85], v[180:183], v[216:219], v[82:85]
	v_mfma_f32_16x16x32_bf16 v[70:73], v[172:175], v[224:227], v[70:73]
	v_mfma_f32_16x16x32_bf16 v[66:69], v[180:183], v[224:227], v[66:69]
	v_mfma_f32_16x16x32_bf16 v[118:121], v[176:179], v[192:195], v[118:121]
	v_mfma_f32_16x16x32_bf16 v[114:117], v[184:187], v[192:195], v[114:117]
	v_mfma_f32_16x16x32_bf16 v[102:105], v[176:179], v[208:211], v[102:105]
	v_mfma_f32_16x16x32_bf16 v[98:101], v[184:187], v[208:211], v[98:101]
	v_mfma_f32_16x16x32_bf16 v[86:89], v[176:179], v[220:223], v[86:89]
	v_mfma_f32_16x16x32_bf16 v[82:85], v[184:187], v[220:223], v[82:85]
	v_mfma_f32_16x16x32_bf16 v[70:73], v[176:179], v[228:231], v[70:73]
	v_mfma_f32_16x16x32_bf16 v[66:69], v[184:187], v[228:231], v[66:69]
	s_setprio 0
	s_barrier
	s_add_i32 s75, s75, s53
	v_lshl_add_u64 v[146:147], s[44:45], 0, v[132:133]
	s_mov_b32 m0, s75
	ds_read_b128 v[188:191], v167 offset:16384
	ds_read_b128 v[192:195], v167 offset:17408
	ds_read_b128 v[196:199], v167 offset:18432
	ds_read_b128 v[208:211], v167 offset:19456
	ds_read_b128 v[216:219], v167 offset:20480
	ds_read_b128 v[220:223], v167 offset:21504
	ds_read_b128 v[224:227], v167 offset:22528
	ds_read_b128 v[228:231], v167 offset:23552
	global_load_lds_dwordx4 v[146:147], off
	s_add_i32 m0, s75, 0x2000
	s_add_u32 s76, s44, 0x40000
	v_lshl_add_u64 v[162:163], s[44:45], 0, v[136:137]
	s_addc_u32 s77, s45, 0
	s_add_i32 s43, s43, s53
	global_load_lds_dwordx4 v[162:163], off
	v_lshl_add_u64 v[200:201], s[76:77], 0, v[132:133]
	s_mov_b32 m0, s43
	v_lshl_add_u64 v[204:205], s[46:47], 0, v[134:135]
	global_load_lds_dwordx4 v[200:201], off
	v_lshl_add_u64 v[200:201], s[76:77], 0, v[136:137]
	s_add_i32 m0, s43, 0x2000
	s_nop 0
	global_load_lds_dwordx4 v[200:201], off
	v_lshl_add_u64 v[200:201], s[46:47], 0, v[130:131]
	s_mov_b32 m0, s59
	s_nop 0
	global_load_lds_dwordx4 v[200:201], off
	s_mov_b32 m0, s62
	s_nop 0
	global_load_lds_dwordx4 v[204:205], off
	s_waitcnt vmcnt(8)
	s_waitcnt lgkmcnt(0)
	s_barrier
; #define PG8_STAGE(bufoff, gbase, voff) do { _Pragma("unroll") for (int _i = 0; _i < 2; ++_i) \
;         __builtin_amdgcn_global_load_lds((const unsigned*)((const char*)(gbase) + (voff)[_i]), (PG8_LAS unsigned*)(lds + (bufoff) + ldsw + _i * 8192), 16, 0, 0); } while (0)
; #define PG8_LDA(dst, b, h) do { _Pragma("unroll") for (int m = 0; m < 4; ++m) _Pragma("unroll") for (int k = 0; k < 2; ++k) dst[m][k] = *(const PG8_LAS bf16x8*)(lds + PG8_SA(b, h) + aoff + m * 2048 + k * 1024); } while (0)
; #define PG8_LDB(dst, b, h) do { _Pragma("unroll") for (int n = 0; n < 2; ++n) _Pragma("unroll") for (int k = 0; k < 2; ++k) dst[n][k] = *(const PG8_LAS bf16x8*)(lds + PG8_SB(b, h) + boff + n * 2048 + k * 1024); } while (0)
; #define PG8_WAIT_V(n) asm volatile("s_waitcnt vmcnt(" #n ")" ::: "memory")
; #define PG8_WAIT_L(n) asm volatile("s_waitcnt lgkmcnt(" #n ")" ::: "memory")
; #define PG8_BAR __builtin_amdgcn_s_barrier()
; #define PG8_SCHED __builtin_amdgcn_sched_barrier(0)
; template <class Epi, bool ALIGN_EPI = true>
; __device__ __forceinline__ void gemm_phase(PG8_LAS unsigned char* lds, const Gemm g, const StaticOrder& S, const Epi& E) {
;     ...
;             PG8_WAIT_V(8); PG8_WAIT_L(0); PG8_BAR; PG8_MMA(1, 0, At, B0); PG8_MMA(1, 1, At, B1); PG8_BAR; PG8_SCHED;
;             PG8_LDB(B0, 1, 0); PG8_LDB(B1, 1, 1); PG8_SCHED; PG8_LDA(At, 1, 0); PG8_STAGE(PG8_SA(0, 1), a2 + hstepA, voffA);
;             PG8_WAIT_V(8); PG8_WAIT_L(0); PG8_BAR; PG8_MMA(0, 0, At, B0); PG8_MMA(0, 1, At, B1); PG8_BAR; PG8_SCHED;
	s_setprio 1
	s_waitcnt lgkmcnt(0)
	v_mfma_f32_16x16x32_bf16 v[62:65], v[142:145], v[188:191], v[62:65]
	v_mfma_f32_16x16x32_bf16 v[58:61], v[158:161], v[188:191], v[58:61]
	v_mfma_f32_16x16x32_bf16 v[46:49], v[142:145], v[196:199], v[46:49]
	v_mfma_f32_16x16x32_bf16 v[42:45], v[158:161], v[196:199], v[42:45]
	v_mfma_f32_16x16x32_bf16 v[28:31], v[142:145], v[216:219], v[28:31]
	v_mfma_f32_16x16x32_bf16 v[24:27], v[158:161], v[216:219], v[24:27]
	v_mfma_f32_16x16x32_bf16 v[12:15], v[142:145], v[224:227], v[12:15]
	v_mfma_f32_16x16x32_bf16 v[8:11], v[158:161], v[224:227], v[8:11]
	v_mfma_f32_16x16x32_bf16 v[62:65], v[148:151], v[192:195], v[62:65]
	v_mfma_f32_16x16x32_bf16 v[58:61], v[168:171], v[192:195], v[58:61]
	v_mfma_f32_16x16x32_bf16 v[46:49], v[148:151], v[208:211], v[46:49]
	v_mfma_f32_16x16x32_bf16 v[42:45], v[168:171], v[208:211], v[42:45]
	v_mfma_f32_16x16x32_bf16 v[28:31], v[148:151], v[220:223], v[28:31]
	v_mfma_f32_16x16x32_bf16 v[24:27], v[168:171], v[220:223], v[24:27]
	v_mfma_f32_16x16x32_bf16 v[12:15], v[148:151], v[228:231], v[12:15]
	v_mfma_f32_16x16x32_bf16 v[8:11], v[168:171], v[228:231], v[8:11]
	s_setprio 0
	s_setprio 1
	v_mfma_f32_16x16x32_bf16 v[54:57], v[172:175], v[188:191], v[54:57]
	v_mfma_f32_16x16x32_bf16 v[50:53], v[180:183], v[188:191], v[50:53]
	v_mfma_f32_16x16x32_bf16 v[38:41], v[172:175], v[196:199], v[38:41]
	v_mfma_f32_16x16x32_bf16 v[34:37], v[180:183], v[196:199], v[34:37]
	v_mfma_f32_16x16x32_bf16 v[20:23], v[172:175], v[216:219], v[20:23]
	v_mfma_f32_16x16x32_bf16 v[16:19], v[180:183], v[216:219], v[16:19]
	v_mfma_f32_16x16x32_bf16 v[4:7], v[172:175], v[224:227], v[4:7]
	v_mfma_f32_16x16x32_bf16 v[0:3], v[180:183], v[224:227], v[0:3]
	v_mfma_f32_16x16x32_bf16 v[54:57], v[176:179], v[192:195], v[54:57]
	v_mfma_f32_16x16x32_bf16 v[50:53], v[184:187], v[192:195], v[50:53]
	v_mfma_f32_16x16x32_bf16 v[38:41], v[176:179], v[208:211], v[38:41]
	v_mfma_f32_16x16x32_bf16 v[34:37], v[184:187], v[208:211], v[34:37]
	v_mfma_f32_16x16x32_bf16 v[20:23], v[176:179], v[220:223], v[20:23]
	v_mfma_f32_16x16x32_bf16 v[16:19], v[184:187], v[220:223], v[16:19]
	v_mfma_f32_16x16x32_bf16 v[4:7], v[176:179], v[228:231], v[4:7]
	v_mfma_f32_16x16x32_bf16 v[0:3], v[184:187], v[228:231], v[0:3]
	s_setprio 0
	s_barrier
	s_add_i32 s43, 0, 0x18000
	v_add_u32_e32 v32, s43, v165
	s_add_i32 s75, 0, 0x1c000
	ds_read_b128 v[142:145], v32
	ds_read_b128 v[148:151], v32 offset:1024
	ds_read_b128 v[158:161], v32 offset:2048
	ds_read_b128 v[168:171], v32 offset:3072
	v_add_u32_e32 v32, s75, v165
	ds_read_b128 v[172:175], v32
	ds_read_b128 v[176:179], v32 offset:1024
	ds_read_b128 v[180:183], v32 offset:2048
	ds_read_b128 v[184:187], v32 offset:3072
	s_add_u32 s46, s46, 0x40000
	s_addc_u32 s47, s47, 0
	s_mov_b32 m0, s63
	v_lshl_add_u64 v[206:207], s[46:47], 0, v[130:131]
	ds_read_b128 v[188:191], v167 offset:32768
	ds_read_b128 v[192:195], v167 offset:33792
	ds_read_b128 v[196:199], v167 offset:34816
	ds_read_b128 v[208:211], v167 offset:35840
	ds_read_b128 v[216:219], v167 offset:36864
	ds_read_b128 v[220:223], v167 offset:37888
	ds_read_b128 v[224:227], v167 offset:38912
	ds_read_b128 v[228:231], v167 offset:39936
	global_load_lds_dwordx4 v[206:207], off
	v_lshl_add_u64 v[206:207], s[46:47], 0, v[134:135]
	s_mov_b32 m0, s66
	s_nop 0
	global_load_lds_dwordx4 v[206:207], off
	s_waitcnt vmcnt(8)
	s_waitcnt lgkmcnt(0)
	s_barrier
	s_setprio 1
	s_waitcnt lgkmcnt(0)
	v_mfma_f32_16x16x32_bf16 v[126:129], v[142:145], v[188:191], v[126:129]
	v_mfma_f32_16x16x32_bf16 v[122:125], v[158:161], v[188:191], v[122:125]
	v_mfma_f32_16x16x32_bf16 v[110:113], v[142:145], v[196:199], v[110:113]
	v_mfma_f32_16x16x32_bf16 v[106:109], v[158:161], v[196:199], v[106:109]
	v_mfma_f32_16x16x32_bf16 v[94:97], v[142:145], v[216:219], v[94:97]
	v_mfma_f32_16x16x32_bf16 v[90:93], v[158:161], v[216:219], v[90:93]
	v_mfma_f32_16x16x32_bf16 v[78:81], v[142:145], v[224:227], v[78:81]
	v_mfma_f32_16x16x32_bf16 v[74:77], v[158:161], v[224:227], v[74:77]
	v_mfma_f32_16x16x32_bf16 v[126:129], v[148:151], v[192:195], v[126:129]
	v_mfma_f32_16x16x32_bf16 v[122:125], v[168:171], v[192:195], v[122:125]
	v_mfma_f32_16x16x32_bf16 v[110:113], v[148:151], v[208:211], v[110:113]
	v_mfma_f32_16x16x32_bf16 v[106:109], v[168:171], v[208:211], v[106:109]
	v_mfma_f32_16x16x32_bf16 v[94:97], v[148:151], v[220:223], v[94:97]
	v_mfma_f32_16x16x32_bf16 v[90:93], v[168:171], v[220:223], v[90:93]
	v_mfma_f32_16x16x32_bf16 v[78:81], v[148:151], v[228:231], v[78:81]
	v_mfma_f32_16x16x32_bf16 v[74:77], v[168:171], v[228:231], v[74:77]
	s_setprio 0
	s_setprio 1
	v_mfma_f32_16x16x32_bf16 v[118:121], v[172:175], v[188:191], v[118:121]
	v_mfma_f32_16x16x32_bf16 v[114:117], v[180:183], v[188:191], v[114:117]
	v_mfma_f32_16x16x32_bf16 v[102:105], v[172:175], v[196:199], v[102:105]
	v_mfma_f32_16x16x32_bf16 v[98:101], v[180:183], v[196:199], v[98:101]
	v_mfma_f32_16x16x32_bf16 v[86:89], v[172:175], v[216:219], v[86:89]
	v_mfma_f32_16x16x32_bf16 v[82:85], v[180:183], v[216:219], v[82:85]
	v_mfma_f32_16x16x32_bf16 v[70:73], v[172:175], v[224:227], v[70:73]
	v_mfma_f32_16x16x32_bf16 v[66:69], v[180:183], v[224:227], v[66:69]
	v_mfma_f32_16x16x32_bf16 v[118:121], v[176:179], v[192:195], v[118:121]
	v_mfma_f32_16x16x32_bf16 v[114:117], v[184:187], v[192:195], v[114:117]
	v_mfma_f32_16x16x32_bf16 v[102:105], v[176:179], v[208:211], v[102:105]
	v_mfma_f32_16x16x32_bf16 v[98:101], v[184:187], v[208:211], v[98:101]
	v_mfma_f32_16x16x32_bf16 v[86:89], v[176:179], v[220:223], v[86:89]
	v_mfma_f32_16x16x32_bf16 v[82:85], v[184:187], v[220:223], v[82:85]
	v_mfma_f32_16x16x32_bf16 v[70:73], v[176:179], v[228:231], v[70:73]
	v_mfma_f32_16x16x32_bf16 v[66:69], v[184:187], v[228:231], v[66:69]
	s_setprio 0
	s_barrier
; #define PG8_STAGE(bufoff, gbase, voff) do { _Pragma("unroll") for (int _i = 0; _i < 2; ++_i) \
;         __builtin_amdgcn_global_load_lds((const unsigned*)((const char*)(gbase) + (voff)[_i]), (PG8_LAS unsigned*)(lds + (bufoff) + ldsw + _i * 8192), 16, 0, 0); } while (0)
; #define PG8_LDA(dst, b, h) do { _Pragma("unroll") for (int m = 0; m < 4; ++m) _Pragma("unroll") for (int k = 0; k < 2; ++k) dst[m][k] = *(const PG8_LAS bf16x8*)(lds + PG8_SA(b, h) + aoff + m * 2048 + k * 1024); } while (0)
; #define PG8_WAIT_V(n) asm volatile("s_waitcnt vmcnt(" #n ")" ::: "memory")
; #define PG8_WAIT_L(n) asm volatile("s_waitcnt lgkmcnt(" #n ")" ::: "memory")
; #define PG8_BAR __builtin_amdgcn_s_barrier()
; #define PG8_SCHED __builtin_amdgcn_sched_barrier(0)
; template <class Epi, bool ALIGN_EPI = true>
; __device__ __forceinline__ void gemm_phase(PG8_LAS unsigned char* lds, const Gemm g, const StaticOrder& S, const Epi& E) {
;     ...
;         for (int t = 0; t < nt; t += 2) {
;             const bool last = (t == nt - 2);
;             const char* a1 = cA + (size_t)(t + 1) * kstep;
;             const char* a2 = last ? nA : cA + (size_t)(t + 2) * kstep; const char* b2 = last ? nB : cB + (size_t)(t + 2) * kstep;
;     ...
;             PG8_LDA(At, 1, 1); PG8_STAGE(PG8_SB(1, 0), b3, voffB); PG8_STAGE(PG8_SB(1, 1), b3 + hstepB, voffB); PG8_STAGE(PG8_SA(1, 0), a3, voffA);
;             PG8_WAIT_V(8); PG8_WAIT_L(0); PG8_BAR; PG8_MMA(1, 0, At, B0); PG8_MMA(1, 1, At, B1); PG8_BAR; PG8_SCHED;
	s_add_i32 s43, s43, s53
	v_lshl_add_u64 v[146:147], v[146:147], 0, s[60:61]
	s_mov_b32 m0, s43
	ds_read_b128 v[188:191], v167 offset:49152
	ds_read_b128 v[192:195], v167 offset:50176
	ds_read_b128 v[196:199], v167 offset:51200
	ds_read_b128 v[208:211], v167 offset:52224
	ds_read_b128 v[216:219], v167 offset:53248
	ds_read_b128 v[220:223], v167 offset:54272
	ds_read_b128 v[224:227], v167 offset:55296
	ds_read_b128 v[228:231], v167 offset:56320
	global_load_lds_dwordx4 v[146:147], off
	s_add_i32 m0, s43, 0x2000
	s_add_u32 s44, s44, 0x40080
	v_lshl_add_u64 v[146:147], v[162:163], 0, s[60:61]
	s_addc_u32 s45, s45, 0
	s_add_i32 s43, s75, s53
	global_load_lds_dwordx4 v[146:147], off
	v_lshl_add_u64 v[146:147], s[44:45], 0, v[132:133]
	s_mov_b32 m0, s43
	s_nop 0
	global_load_lds_dwordx4 v[146:147], off
	v_lshl_add_u64 v[146:147], s[44:45], 0, v[136:137]
	s_add_i32 m0, s43, 0x2000
	s_nop 0
	global_load_lds_dwordx4 v[146:147], off
	v_lshl_add_u64 v[146:147], v[200:201], 0, s[60:61]
	s_mov_b32 m0, s70
	s_nop 0
	global_load_lds_dwordx4 v[146:147], off
	v_lshl_add_u64 v[146:147], v[204:205], 0, s[60:61]
	s_mov_b32 m0, s71
	s_nop 0
	global_load_lds_dwordx4 v[146:147], off
	s_add_i32 s37, s37, 2
	s_add_u32 s6, s6, 0x100
	s_addc_u32 s7, s7, 0
	s_add_u32 s9, s9, 0x100
	s_addc_u32 s35, s35, 0
	s_add_u32 s43, s6, 0xfffc0080
	s_addc_u32 s44, s7, -1
	s_add_i32 s75, 0, 0x10000
	s_cmp_eq_u32 s37, 12
	s_cselect_b32 s47, s39, s44
	s_cselect_b32 s46, s38, s43
	v_add_u32_e32 v32, s75, v165
	s_cselect_b32 s45, s41, s35
	s_cselect_b32 s44, s40, s9
	s_add_i32 s43, 0, 0x14000
	s_cmp_gt_u32 s37, 13
	s_waitcnt vmcnt(8)
	s_waitcnt lgkmcnt(0)
	s_barrier
	s_setprio 1
	s_waitcnt lgkmcnt(0)
	v_mfma_f32_16x16x32_bf16 v[62:65], v[142:145], v[188:191], v[62:65]
	v_mfma_f32_16x16x32_bf16 v[58:61], v[158:161], v[188:191], v[58:61]
	v_mfma_f32_16x16x32_bf16 v[46:49], v[142:145], v[196:199], v[46:49]
	v_mfma_f32_16x16x32_bf16 v[42:45], v[158:161], v[196:199], v[42:45]
	v_mfma_f32_16x16x32_bf16 v[28:31], v[142:145], v[216:219], v[28:31]
	v_mfma_f32_16x16x32_bf16 v[24:27], v[158:161], v[216:219], v[24:27]
	v_mfma_f32_16x16x32_bf16 v[12:15], v[142:145], v[224:227], v[12:15]
	v_mfma_f32_16x16x32_bf16 v[8:11], v[158:161], v[224:227], v[8:11]
	v_mfma_f32_16x16x32_bf16 v[62:65], v[148:151], v[192:195], v[62:65]
	v_mfma_f32_16x16x32_bf16 v[58:61], v[168:171], v[192:195], v[58:61]
	v_mfma_f32_16x16x32_bf16 v[46:49], v[148:151], v[208:211], v[46:49]
	v_mfma_f32_16x16x32_bf16 v[42:45], v[168:171], v[208:211], v[42:45]
	v_mfma_f32_16x16x32_bf16 v[28:31], v[148:151], v[220:223], v[28:31]
	v_mfma_f32_16x16x32_bf16 v[24:27], v[168:171], v[220:223], v[24:27]
	v_mfma_f32_16x16x32_bf16 v[12:15], v[148:151], v[228:231], v[12:15]
	v_mfma_f32_16x16x32_bf16 v[8:11], v[168:171], v[228:231], v[8:11]
	s_setprio 0
	s_setprio 1
	v_mfma_f32_16x16x32_bf16 v[54:57], v[172:175], v[188:191], v[54:57]
	v_mfma_f32_16x16x32_bf16 v[50:53], v[180:183], v[188:191], v[50:53]
	v_mfma_f32_16x16x32_bf16 v[38:41], v[172:175], v[196:199], v[38:41]
	v_mfma_f32_16x16x32_bf16 v[34:37], v[180:183], v[196:199], v[34:37]
	v_mfma_f32_16x16x32_bf16 v[20:23], v[172:175], v[216:219], v[20:23]
	v_mfma_f32_16x16x32_bf16 v[16:19], v[180:183], v[216:219], v[16:19]
	v_mfma_f32_16x16x32_bf16 v[4:7], v[172:175], v[224:227], v[4:7]
	v_mfma_f32_16x16x32_bf16 v[0:3], v[180:183], v[224:227], v[0:3]
	v_mfma_f32_16x16x32_bf16 v[54:57], v[176:179], v[192:195], v[54:57]
	v_mfma_f32_16x16x32_bf16 v[50:53], v[184:187], v[192:195], v[50:53]
	v_mfma_f32_16x16x32_bf16 v[38:41], v[176:179], v[208:211], v[38:41]
	v_mfma_f32_16x16x32_bf16 v[34:37], v[184:187], v[208:211], v[34:37]
	v_mfma_f32_16x16x32_bf16 v[20:23], v[176:179], v[220:223], v[20:23]
	v_mfma_f32_16x16x32_bf16 v[16:19], v[184:187], v[220:223], v[16:19]
	v_mfma_f32_16x16x32_bf16 v[4:7], v[176:179], v[228:231], v[4:7]
	v_mfma_f32_16x16x32_bf16 v[0:3], v[184:187], v[228:231], v[0:3]
	s_setprio 0
	s_barrier
	s_cbranch_scc0 .Lrot_1829
	s_and_b64 vcc, exec, s[26:27]
	s_cbranch_vccz .LBB0_1832
	s_barrier

; #define PG8_STAGE(bufoff, gbase, voff) do { _Pragma("unroll") for (int _i = 0; _i < 2; ++_i) \
;         __builtin_amdgcn_global_load_lds((const unsigned*)((const char*)(gbase) + (voff)[_i]), (PG8_LAS unsigned*)(lds + (bufoff) + ldsw + _i * 8192), 16, 0, 0); } while (0)
; #define PG8_LDA(dst, b, h) do { _Pragma("unroll") for (int m = 0; m < 4; ++m) _Pragma("unroll") for (int k = 0; k < 2; ++k) dst[m][k] = *(const PG8_LAS bf16x8*)(lds + PG8_SA(b, h) + aoff + m * 2048 + k * 1024); } while (0)
; #define PG8_LDB(dst, b, h) do { _Pragma("unroll") for (int n = 0; n < 2; ++n) _Pragma("unroll") for (int k = 0; k < 2; ++k) dst[n][k] = *(const PG8_LAS bf16x8*)(lds + PG8_SB(b, h) + boff + n * 2048 + k * 1024); } while (0)
; #define PG8_WAIT_V(n) asm volatile("s_waitcnt vmcnt(" #n ")" ::: "memory")
; #define PG8_WAIT_L(n) asm volatile("s_waitcnt lgkmcnt(" #n ")" ::: "memory")
; #define PG8_BAR __builtin_amdgcn_s_barrier()
; #define PG8_SCHED __builtin_amdgcn_sched_barrier(0)
; template <class Epi, bool ALIGN_EPI = true>
; __device__ __forceinline__ void gemm_phase(PG8_LAS unsigned char* lds, const Gemm g, const StaticOrder& S, const Epi& E) {
;     ...
;             PG8_LDB(B0, 0, 0); PG8_LDB(B1, 0, 1); PG8_SCHED; PG8_LDA(At, 0, 0); PG8_STAGE(PG8_SA(1, 1), a1 + hstepA, voffA);
;             PG8_WAIT_V(8); PG8_WAIT_L(0); PG8_BAR; PG8_MMA(0, 0, At, B0); PG8_MMA(0, 1, At, B1); PG8_BAR; PG8_SCHED;
;             PG8_LDA(At, 0, 1); PG8_STAGE(PG8_SB(0, 0), b2, voffB); PG8_STAGE(PG8_SB(0, 1), b2 + hstepB, voffB); PG8_STAGE(PG8_SA(0, 0), a2, voffA);
.Lrot_2032:
	ds_read_b128 v[140:143], v144
	ds_read_b128 v[148:151], v144 offset:1024
	ds_read_b128 v[162:165], v144 offset:2048
	ds_read_b128 v[166:169], v144 offset:3072
	v_add_u32_e32 v144, s90, v159
	ds_read_b128 v[170:173], v144
	ds_read_b128 v[174:177], v144 offset:1024
	ds_read_b128 v[178:181], v144 offset:2048
	ds_read_b128 v[182:185], v144 offset:3072
	v_lshl_add_u64 v[144:145], s[40:41], 0, v[136:137]
	s_add_i32 m0, s39, 0xc000
	ds_read_b128 v[186:189], v161
	ds_read_b128 v[190:193], v161 offset:1024
	ds_read_b128 v[194:197], v161 offset:2048
	ds_read_b128 v[198:201], v161 offset:3072
	ds_read_b128 v[208:211], v161 offset:4096
	ds_read_b128 v[216:219], v161 offset:5120
	ds_read_b128 v[220:223], v161 offset:6144
	ds_read_b128 v[224:227], v161 offset:7168
	global_load_lds_dwordx4 v[144:145], off
	v_lshl_add_u64 v[144:145], s[40:41], 0, v[138:139]
	s_add_i32 m0, s39, 0xe000
	s_nop 0
	global_load_lds_dwordx4 v[144:145], off
	s_waitcnt vmcnt(8)
	s_waitcnt lgkmcnt(0)
	s_barrier
	s_setprio 1
	s_waitcnt lgkmcnt(0)
	v_mfma_f32_16x16x32_bf16 v[126:129], v[140:143], v[186:189], v[126:129]
	v_mfma_f32_16x16x32_bf16 v[122:125], v[162:165], v[186:189], v[122:125]
	v_mfma_f32_16x16x32_bf16 v[110:113], v[140:143], v[194:197], v[110:113]
	v_mfma_f32_16x16x32_bf16 v[106:109], v[162:165], v[194:197], v[106:109]
	v_mfma_f32_16x16x32_bf16 v[94:97], v[140:143], v[208:211], v[94:97]
	v_mfma_f32_16x16x32_bf16 v[90:93], v[162:165], v[208:211], v[90:93]
	v_mfma_f32_16x16x32_bf16 v[78:81], v[140:143], v[220:223], v[78:81]
	v_mfma_f32_16x16x32_bf16 v[74:77], v[162:165], v[220:223], v[74:77]
	v_mfma_f32_16x16x32_bf16 v[126:129], v[148:151], v[190:193], v[126:129]
	v_mfma_f32_16x16x32_bf16 v[122:125], v[166:169], v[190:193], v[122:125]
	v_mfma_f32_16x16x32_bf16 v[110:113], v[148:151], v[198:201], v[110:113]
	v_mfma_f32_16x16x32_bf16 v[106:109], v[166:169], v[198:201], v[106:109]
	v_mfma_f32_16x16x32_bf16 v[94:97], v[148:151], v[216:219], v[94:97]
	v_mfma_f32_16x16x32_bf16 v[90:93], v[166:169], v[216:219], v[90:93]
	v_mfma_f32_16x16x32_bf16 v[78:81], v[148:151], v[224:227], v[78:81]
	v_mfma_f32_16x16x32_bf16 v[74:77], v[166:169], v[224:227], v[74:77]
	s_setprio 0
	s_setprio 1
	v_mfma_f32_16x16x32_bf16 v[118:121], v[170:173], v[186:189], v[118:121]
	v_mfma_f32_16x16x32_bf16 v[114:117], v[178:181], v[186:189], v[114:117]
	v_mfma_f32_16x16x32_bf16 v[102:105], v[170:173], v[194:197], v[102:105]
	v_mfma_f32_16x16x32_bf16 v[98:101], v[178:181], v[194:197], v[98:101]
	v_mfma_f32_16x16x32_bf16 v[86:89], v[170:173], v[208:211], v[86:89]
	v_mfma_f32_16x16x32_bf16 v[82:85], v[178:181], v[208:211], v[82:85]
	v_mfma_f32_16x16x32_bf16 v[70:73], v[170:173], v[220:223], v[70:73]
	v_mfma_f32_16x16x32_bf16 v[66:69], v[178:181], v[220:223], v[66:69]
	v_mfma_f32_16x16x32_bf16 v[118:121], v[174:177], v[190:193], v[118:121]
	v_mfma_f32_16x16x32_bf16 v[114:117], v[182:185], v[190:193], v[114:117]
	v_mfma_f32_16x16x32_bf16 v[102:105], v[174:177], v[198:201], v[102:105]
	v_mfma_f32_16x16x32_bf16 v[98:101], v[182:185], v[198:201], v[98:101]
	v_mfma_f32_16x16x32_bf16 v[86:89], v[174:177], v[216:219], v[86:89]
	v_mfma_f32_16x16x32_bf16 v[82:85], v[182:185], v[216:219], v[82:85]
	v_mfma_f32_16x16x32_bf16 v[70:73], v[174:177], v[224:227], v[70:73]
	v_mfma_f32_16x16x32_bf16 v[66:69], v[182:185], v[224:227], v[66:69]
	s_setprio 0
	s_barrier
	s_add_i32 s87, s87, s53
	v_lshl_add_u64 v[144:145], s[42:43], 0, v[32:33]
	s_mov_b32 m0, s87
	ds_read_b128 v[186:189], v161 offset:16384
	ds_read_b128 v[190:193], v161 offset:17408
	ds_read_b128 v[194:197], v161 offset:18432
	ds_read_b128 v[198:201], v161 offset:19456
	ds_read_b128 v[208:211], v161 offset:20480
	ds_read_b128 v[216:219], v161 offset:21504
	ds_read_b128 v[220:223], v161 offset:22528
	ds_read_b128 v[224:227], v161 offset:23552
	global_load_lds_dwordx4 v[144:145], off
	s_add_i32 m0, s87, 0x2000
	s_add_u32 s88, s42, 0x40000
	v_lshl_add_u64 v[146:147], s[42:43], 0, v[134:135]
	s_addc_u32 s89, s43, 0
	s_add_i32 s87, s90, s53
	global_load_lds_dwordx4 v[146:147], off
	v_lshl_add_u64 v[204:205], s[88:89], 0, v[32:33]
	s_mov_b32 m0, s87
	v_lshl_add_u64 v[206:207], s[44:45], 0, v[132:133]
	global_load_lds_dwordx4 v[204:205], off
	v_lshl_add_u64 v[204:205], s[88:89], 0, v[134:135]
	s_add_i32 m0, s87, 0x2000
	s_nop 0
	global_load_lds_dwordx4 v[204:205], off
	v_lshl_add_u64 v[204:205], s[44:45], 0, v[130:131]
	s_mov_b32 m0, s39
	s_nop 0
	global_load_lds_dwordx4 v[204:205], off
	s_mov_b32 m0, s67
	s_nop 0
	global_load_lds_dwordx4 v[206:207], off
	s_waitcnt vmcnt(8)
	s_waitcnt lgkmcnt(0)
	s_barrier
; #define PG8_STAGE(bufoff, gbase, voff) do { _Pragma("unroll") for (int _i = 0; _i < 2; ++_i) \
;         __builtin_amdgcn_global_load_lds((const unsigned*)((const char*)(gbase) + (voff)[_i]), (PG8_LAS unsigned*)(lds + (bufoff) + ldsw + _i * 8192), 16, 0, 0); } while (0)
; #define PG8_LDA(dst, b, h) do { _Pragma("unroll") for (int m = 0; m < 4; ++m) _Pragma("unroll") for (int k = 0; k < 2; ++k) dst[m][k] = *(const PG8_LAS bf16x8*)(lds + PG8_SA(b, h) + aoff + m * 2048 + k * 1024); } while (0)
; #define PG8_LDB(dst, b, h) do { _Pragma("unroll") for (int n = 0; n < 2; ++n) _Pragma("unroll") for (int k = 0; k < 2; ++k) dst[n][k] = *(const PG8_LAS bf16x8*)(lds + PG8_SB(b, h) + boff + n * 2048 + k * 1024); } while (0)
; #define PG8_WAIT_V(n) asm volatile("s_waitcnt vmcnt(" #n ")" ::: "memory")
; #define PG8_WAIT_L(n) asm volatile("s_waitcnt lgkmcnt(" #n ")" ::: "memory")
; #define PG8_BAR __builtin_amdgcn_s_barrier()
; #define PG8_SCHED __builtin_amdgcn_sched_barrier(0)
; template <class Epi, bool ALIGN_EPI = true>
; __device__ __forceinline__ void gemm_phase(PG8_LAS unsigned char* lds, const Gemm g, const StaticOrder& S, const Epi& E) {
;     ...
;             PG8_WAIT_V(8); PG8_WAIT_L(0); PG8_BAR; PG8_MMA(1, 0, At, B0); PG8_MMA(1, 1, At, B1); PG8_BAR; PG8_SCHED;
;             PG8_LDB(B0, 1, 0); PG8_LDB(B1, 1, 1); PG8_SCHED; PG8_LDA(At, 1, 0); PG8_STAGE(PG8_SA(0, 1), a2 + hstepA, voffA);
;             PG8_WAIT_V(8); PG8_WAIT_L(0); PG8_BAR; PG8_MMA(0, 0, At, B0); PG8_MMA(0, 1, At, B1); PG8_BAR; PG8_SCHED;
	s_setprio 1
	s_waitcnt lgkmcnt(0)
	v_mfma_f32_16x16x32_bf16 v[62:65], v[140:143], v[186:189], v[62:65]
	v_mfma_f32_16x16x32_bf16 v[58:61], v[162:165], v[186:189], v[58:61]
	v_mfma_f32_16x16x32_bf16 v[46:49], v[140:143], v[194:197], v[46:49]
	v_mfma_f32_16x16x32_bf16 v[42:45], v[162:165], v[194:197], v[42:45]
	v_mfma_f32_16x16x32_bf16 v[28:31], v[140:143], v[208:211], v[28:31]
	v_mfma_f32_16x16x32_bf16 v[24:27], v[162:165], v[208:211], v[24:27]
	v_mfma_f32_16x16x32_bf16 v[12:15], v[140:143], v[220:223], v[12:15]
	v_mfma_f32_16x16x32_bf16 v[8:11], v[162:165], v[220:223], v[8:11]
	v_mfma_f32_16x16x32_bf16 v[62:65], v[148:151], v[190:193], v[62:65]
	v_mfma_f32_16x16x32_bf16 v[58:61], v[166:169], v[190:193], v[58:61]
	v_mfma_f32_16x16x32_bf16 v[46:49], v[148:151], v[198:201], v[46:49]
	v_mfma_f32_16x16x32_bf16 v[42:45], v[166:169], v[198:201], v[42:45]
	v_mfma_f32_16x16x32_bf16 v[28:31], v[148:151], v[216:219], v[28:31]
	v_mfma_f32_16x16x32_bf16 v[24:27], v[166:169], v[216:219], v[24:27]
	v_mfma_f32_16x16x32_bf16 v[12:15], v[148:151], v[224:227], v[12:15]
	v_mfma_f32_16x16x32_bf16 v[8:11], v[166:169], v[224:227], v[8:11]
	s_setprio 0
	s_setprio 1
	v_mfma_f32_16x16x32_bf16 v[54:57], v[170:173], v[186:189], v[54:57]
	v_mfma_f32_16x16x32_bf16 v[50:53], v[178:181], v[186:189], v[50:53]
	v_mfma_f32_16x16x32_bf16 v[38:41], v[170:173], v[194:197], v[38:41]
	v_mfma_f32_16x16x32_bf16 v[34:37], v[178:181], v[194:197], v[34:37]
	v_mfma_f32_16x16x32_bf16 v[20:23], v[170:173], v[208:211], v[20:23]
	v_mfma_f32_16x16x32_bf16 v[16:19], v[178:181], v[208:211], v[16:19]
	v_mfma_f32_16x16x32_bf16 v[4:7], v[170:173], v[220:223], v[4:7]
	v_mfma_f32_16x16x32_bf16 v[0:3], v[178:181], v[220:223], v[0:3]
	v_mfma_f32_16x16x32_bf16 v[54:57], v[174:177], v[190:193], v[54:57]
	v_mfma_f32_16x16x32_bf16 v[50:53], v[182:185], v[190:193], v[50:53]
	v_mfma_f32_16x16x32_bf16 v[38:41], v[174:177], v[198:201], v[38:41]
	v_mfma_f32_16x16x32_bf16 v[34:37], v[182:185], v[198:201], v[34:37]
	v_mfma_f32_16x16x32_bf16 v[20:23], v[174:177], v[216:219], v[20:23]
	v_mfma_f32_16x16x32_bf16 v[16:19], v[182:185], v[216:219], v[16:19]
	v_mfma_f32_16x16x32_bf16 v[4:7], v[174:177], v[224:227], v[4:7]
	v_mfma_f32_16x16x32_bf16 v[0:3], v[182:185], v[224:227], v[0:3]
	s_setprio 0
	s_barrier
	s_add_i32 s87, 0, 0x18000
	v_add_u32_e32 v154, s87, v159
	s_add_i32 s88, 0, 0x1c000
	ds_read_b128 v[140:143], v154
	ds_read_b128 v[148:151], v154 offset:1024
	ds_read_b128 v[162:165], v154 offset:2048
	ds_read_b128 v[166:169], v154 offset:3072
	v_add_u32_e32 v154, s88, v159
	ds_read_b128 v[170:173], v154
	ds_read_b128 v[174:177], v154 offset:1024
	ds_read_b128 v[178:181], v154 offset:2048
	ds_read_b128 v[182:185], v154 offset:3072
	s_add_u32 s44, s44, 0x40000
	s_addc_u32 s45, s45, 0
	s_mov_b32 m0, s70
	v_lshl_add_u64 v[228:229], s[44:45], 0, v[130:131]
	ds_read_b128 v[186:189], v161 offset:32768
	ds_read_b128 v[190:193], v161 offset:33792
	ds_read_b128 v[194:197], v161 offset:34816
	ds_read_b128 v[198:201], v161 offset:35840
	ds_read_b128 v[208:211], v161 offset:36864
	ds_read_b128 v[216:219], v161 offset:37888
	ds_read_b128 v[220:223], v161 offset:38912
	ds_read_b128 v[224:227], v161 offset:39936
	global_load_lds_dwordx4 v[228:229], off
	v_lshl_add_u64 v[228:229], s[44:45], 0, v[132:133]
	s_mov_b32 m0, s71
	s_nop 0
	global_load_lds_dwordx4 v[228:229], off
	s_waitcnt vmcnt(8)
	s_waitcnt lgkmcnt(0)
	s_barrier
	s_setprio 1
	s_waitcnt lgkmcnt(0)
	v_mfma_f32_16x16x32_bf16 v[126:129], v[140:143], v[186:189], v[126:129]
	v_mfma_f32_16x16x32_bf16 v[122:125], v[162:165], v[186:189], v[122:125]
	v_mfma_f32_16x16x32_bf16 v[110:113], v[140:143], v[194:197], v[110:113]
	v_mfma_f32_16x16x32_bf16 v[106:109], v[162:165], v[194:197], v[106:109]
	v_mfma_f32_16x16x32_bf16 v[94:97], v[140:143], v[208:211], v[94:97]
	v_mfma_f32_16x16x32_bf16 v[90:93], v[162:165], v[208:211], v[90:93]
	v_mfma_f32_16x16x32_bf16 v[78:81], v[140:143], v[220:223], v[78:81]
	v_mfma_f32_16x16x32_bf16 v[74:77], v[162:165], v[220:223], v[74:77]
	v_mfma_f32_16x16x32_bf16 v[126:129], v[148:151], v[190:193], v[126:129]
	v_mfma_f32_16x16x32_bf16 v[122:125], v[166:169], v[190:193], v[122:125]
	v_mfma_f32_16x16x32_bf16 v[110:113], v[148:151], v[198:201], v[110:113]
	v_mfma_f32_16x16x32_bf16 v[106:109], v[166:169], v[198:201], v[106:109]
	v_mfma_f32_16x16x32_bf16 v[94:97], v[148:151], v[216:219], v[94:97]
	v_mfma_f32_16x16x32_bf16 v[90:93], v[166:169], v[216:219], v[90:93]
	v_mfma_f32_16x16x32_bf16 v[78:81], v[148:151], v[224:227], v[78:81]
	v_mfma_f32_16x16x32_bf16 v[74:77], v[166:169], v[224:227], v[74:77]
	s_setprio 0
	s_setprio 1
	v_mfma_f32_16x16x32_bf16 v[118:121], v[170:173], v[186:189], v[118:121]
	v_mfma_f32_16x16x32_bf16 v[114:117], v[178:181], v[186:189], v[114:117]
	v_mfma_f32_16x16x32_bf16 v[102:105], v[170:173], v[194:197], v[102:105]
	v_mfma_f32_16x16x32_bf16 v[98:101], v[178:181], v[194:197], v[98:101]
	v_mfma_f32_16x16x32_bf16 v[86:89], v[170:173], v[208:211], v[86:89]
	v_mfma_f32_16x16x32_bf16 v[82:85], v[178:181], v[208:211], v[82:85]
	v_mfma_f32_16x16x32_bf16 v[70:73], v[170:173], v[220:223], v[70:73]
	v_mfma_f32_16x16x32_bf16 v[66:69], v[178:181], v[220:223], v[66:69]
	v_mfma_f32_16x16x32_bf16 v[118:121], v[174:177], v[190:193], v[118:121]
	v_mfma_f32_16x16x32_bf16 v[114:117], v[182:185], v[190:193], v[114:117]
	v_mfma_f32_16x16x32_bf16 v[102:105], v[174:177], v[198:201], v[102:105]
	v_mfma_f32_16x16x32_bf16 v[98:101], v[182:185], v[198:201], v[98:101]
	v_mfma_f32_16x16x32_bf16 v[86:89], v[174:177], v[216:219], v[86:89]
	v_mfma_f32_16x16x32_bf16 v[82:85], v[182:185], v[216:219], v[82:85]
	v_mfma_f32_16x16x32_bf16 v[70:73], v[174:177], v[224:227], v[70:73]
	v_mfma_f32_16x16x32_bf16 v[66:69], v[182:185], v[224:227], v[66:69]
	s_setprio 0
	s_barrier
; #define PG8_STAGE(bufoff, gbase, voff) do { _Pragma("unroll") for (int _i = 0; _i < 2; ++_i) \
;         __builtin_amdgcn_global_load_lds((const unsigned*)((const char*)(gbase) + (voff)[_i]), (PG8_LAS unsigned*)(lds + (bufoff) + ldsw + _i * 8192), 16, 0, 0); } while (0)
; #define PG8_LDA(dst, b, h) do { _Pragma("unroll") for (int m = 0; m < 4; ++m) _Pragma("unroll") for (int k = 0; k < 2; ++k) dst[m][k] = *(const PG8_LAS bf16x8*)(lds + PG8_SA(b, h) + aoff + m * 2048 + k * 1024); } while (0)
; #define PG8_WAIT_V(n) asm volatile("s_waitcnt vmcnt(" #n ")" ::: "memory")
; #define PG8_WAIT_L(n) asm volatile("s_waitcnt lgkmcnt(" #n ")" ::: "memory")
; #define PG8_BAR __builtin_amdgcn_s_barrier()
; #define PG8_SCHED __builtin_amdgcn_sched_barrier(0)
; template <class Epi, bool ALIGN_EPI = true>
; __device__ __forceinline__ void gemm_phase(PG8_LAS unsigned char* lds, const Gemm g, const StaticOrder& S, const Epi& E) {
;     ...
;         for (int t = 0; t < nt; t += 2) {
;             const bool last = (t == nt - 2);
;             const char* a1 = cA + (size_t)(t + 1) * kstep;
;             const char* a2 = last ? nA : cA + (size_t)(t + 2) * kstep; const char* b2 = last ? nB : cB + (size_t)(t + 2) * kstep;
;     ...
;             PG8_LDA(At, 1, 1); PG8_STAGE(PG8_SB(1, 0), b3, voffB); PG8_STAGE(PG8_SB(1, 1), b3 + hstepB, voffB); PG8_STAGE(PG8_SA(1, 0), a3, voffA);
;             PG8_WAIT_V(8); PG8_WAIT_L(0); PG8_BAR; PG8_MMA(1, 0, At, B0); PG8_MMA(1, 1, At, B1); PG8_BAR; PG8_SCHED;
	s_add_i32 s44, s87, s53
	v_lshl_add_u64 v[144:145], v[144:145], 0, s[60:61]
	s_mov_b32 m0, s44
	ds_read_b128 v[186:189], v161 offset:49152
	ds_read_b128 v[190:193], v161 offset:50176
	ds_read_b128 v[194:197], v161 offset:51200
	ds_read_b128 v[198:201], v161 offset:52224
	ds_read_b128 v[208:211], v161 offset:53248
	ds_read_b128 v[216:219], v161 offset:54272
	ds_read_b128 v[220:223], v161 offset:55296
	ds_read_b128 v[224:227], v161 offset:56320
	global_load_lds_dwordx4 v[144:145], off
	s_add_i32 m0, s44, 0x2000
	s_add_u32 s42, s42, 0x40080
	v_lshl_add_u64 v[144:145], v[146:147], 0, s[60:61]
	s_addc_u32 s43, s43, 0
	s_add_i32 s44, s88, s53
	global_load_lds_dwordx4 v[144:145], off
	v_lshl_add_u64 v[144:145], s[42:43], 0, v[32:33]
	s_mov_b32 m0, s44
	s_nop 0
	global_load_lds_dwordx4 v[144:145], off
	v_lshl_add_u64 v[144:145], s[42:43], 0, v[134:135]
	s_add_i32 m0, s44, 0x2000
	s_nop 0
	global_load_lds_dwordx4 v[144:145], off
	v_lshl_add_u64 v[144:145], v[204:205], 0, s[60:61]
	s_mov_b32 m0, s72
	s_nop 0
	global_load_lds_dwordx4 v[144:145], off
	v_lshl_add_u64 v[144:145], v[206:207], 0, s[60:61]
	s_mov_b32 m0, s73
	s_nop 0
	global_load_lds_dwordx4 v[144:145], off
	s_add_i32 s86, s86, 2
	s_add_u32 s40, s40, 0x100
	s_addc_u32 s41, s41, 0
	s_add_u32 s83, s83, 0x100
	s_addc_u32 s85, s85, 0
	s_add_u32 s42, s40, 0xfffc0080
	s_addc_u32 s43, s41, -1
	s_add_i32 s87, 0, 0x10000
	s_cmp_eq_u32 s86, 12
	s_cselect_b32 s45, s29, s43
	s_cselect_b32 s44, s37, s42
	v_add_u32_e32 v144, s87, v159
	s_cselect_b32 s43, s27, s85
	s_cselect_b32 s42, s82, s83
	s_add_i32 s90, 0, 0x14000
	s_cmp_gt_u32 s86, 13
	s_waitcnt vmcnt(8)
	s_waitcnt lgkmcnt(0)
	s_barrier
	s_setprio 1
	s_waitcnt lgkmcnt(0)
	v_mfma_f32_16x16x32_bf16 v[62:65], v[140:143], v[186:189], v[62:65]
	v_mfma_f32_16x16x32_bf16 v[58:61], v[162:165], v[186:189], v[58:61]
	v_mfma_f32_16x16x32_bf16 v[46:49], v[140:143], v[194:197], v[46:49]
	v_mfma_f32_16x16x32_bf16 v[42:45], v[162:165], v[194:197], v[42:45]
	v_mfma_f32_16x16x32_bf16 v[28:31], v[140:143], v[208:211], v[28:31]
	v_mfma_f32_16x16x32_bf16 v[24:27], v[162:165], v[208:211], v[24:27]
	v_mfma_f32_16x16x32_bf16 v[12:15], v[140:143], v[220:223], v[12:15]
	v_mfma_f32_16x16x32_bf16 v[8:11], v[162:165], v[220:223], v[8:11]
	v_mfma_f32_16x16x32_bf16 v[62:65], v[148:151], v[190:193], v[62:65]
	v_mfma_f32_16x16x32_bf16 v[58:61], v[166:169], v[190:193], v[58:61]
	v_mfma_f32_16x16x32_bf16 v[46:49], v[148:151], v[198:201], v[46:49]
	v_mfma_f32_16x16x32_bf16 v[42:45], v[166:169], v[198:201], v[42:45]
	v_mfma_f32_16x16x32_bf16 v[28:31], v[148:151], v[216:219], v[28:31]
	v_mfma_f32_16x16x32_bf16 v[24:27], v[166:169], v[216:219], v[24:27]
	v_mfma_f32_16x16x32_bf16 v[12:15], v[148:151], v[224:227], v[12:15]
	v_mfma_f32_16x16x32_bf16 v[8:11], v[166:169], v[224:227], v[8:11]
	s_setprio 0
	s_setprio 1
	v_mfma_f32_16x16x32_bf16 v[54:57], v[170:173], v[186:189], v[54:57]
	v_mfma_f32_16x16x32_bf16 v[50:53], v[178:181], v[186:189], v[50:53]
	v_mfma_f32_16x16x32_bf16 v[38:41], v[170:173], v[194:197], v[38:41]
	v_mfma_f32_16x16x32_bf16 v[34:37], v[178:181], v[194:197], v[34:37]
	v_mfma_f32_16x16x32_bf16 v[20:23], v[170:173], v[208:211], v[20:23]
	v_mfma_f32_16x16x32_bf16 v[16:19], v[178:181], v[208:211], v[16:19]
	v_mfma_f32_16x16x32_bf16 v[4:7], v[170:173], v[220:223], v[4:7]
	v_mfma_f32_16x16x32_bf16 v[0:3], v[178:181], v[220:223], v[0:3]
	v_mfma_f32_16x16x32_bf16 v[54:57], v[174:177], v[190:193], v[54:57]
	v_mfma_f32_16x16x32_bf16 v[50:53], v[182:185], v[190:193], v[50:53]
	v_mfma_f32_16x16x32_bf16 v[38:41], v[174:177], v[198:201], v[38:41]
	v_mfma_f32_16x16x32_bf16 v[34:37], v[182:185], v[198:201], v[34:37]
	v_mfma_f32_16x16x32_bf16 v[20:23], v[174:177], v[216:219], v[20:23]
	v_mfma_f32_16x16x32_bf16 v[16:19], v[182:185], v[216:219], v[16:19]
	v_mfma_f32_16x16x32_bf16 v[4:7], v[174:177], v[224:227], v[4:7]
	v_mfma_f32_16x16x32_bf16 v[0:3], v[182:185], v[224:227], v[0:3]
	s_setprio 0
	s_barrier
	s_cbranch_scc0 .Lrot_2032
	s_and_b64 vcc, exec, s[14:15]
	s_cbranch_vccz .LBB0_2035
	s_barrier

; #define PG8_STAGE(bufoff, gbase, voff) do { _Pragma("unroll") for (int _i = 0; _i < 2; ++_i) \
;         __builtin_amdgcn_global_load_lds((const unsigned*)((const char*)(gbase) + (voff)[_i]), (PG8_LAS unsigned*)(lds + (bufoff) + ldsw + _i * 8192), 16, 0, 0); } while (0)
; #define PG8_LDA(dst, b, h) do { _Pragma("unroll") for (int m = 0; m < 4; ++m) _Pragma("unroll") for (int k = 0; k < 2; ++k) dst[m][k] = *(const PG8_LAS bf16x8*)(lds + PG8_SA(b, h) + aoff + m * 2048 + k * 1024); } while (0)
; #define PG8_LDB(dst, b, h) do { _Pragma("unroll") for (int n = 0; n < 2; ++n) _Pragma("unroll") for (int k = 0; k < 2; ++k) dst[n][k] = *(const PG8_LAS bf16x8*)(lds + PG8_SB(b, h) + boff + n * 2048 + k * 1024); } while (0)
; #define PG8_WAIT_V(n) asm volatile("s_waitcnt vmcnt(" #n ")" ::: "memory")
; #define PG8_WAIT_L(n) asm volatile("s_waitcnt lgkmcnt(" #n ")" ::: "memory")
; #define PG8_BAR __builtin_amdgcn_s_barrier()
; #define PG8_SCHED __builtin_amdgcn_sched_barrier(0)
; template <class Epi, bool ALIGN_EPI = true>
; __device__ __forceinline__ void gemm_phase(PG8_LAS unsigned char* lds, const Gemm g, const StaticOrder& S, const Epi& E) {
;     ...
;             PG8_LDB(B0, 0, 0); PG8_LDB(B1, 0, 1); PG8_SCHED; PG8_LDA(At, 0, 0); PG8_STAGE(PG8_SA(1, 1), a1 + hstepA, voffA);
;             PG8_WAIT_V(8); PG8_WAIT_L(0); PG8_BAR; PG8_MMA(0, 0, At, B0); PG8_MMA(0, 1, At, B1); PG8_BAR; PG8_SCHED;
;             PG8_LDA(At, 0, 1); PG8_STAGE(PG8_SB(0, 0), b2, voffB); PG8_STAGE(PG8_SB(0, 1), b2 + hstepB, voffB); PG8_STAGE(PG8_SA(0, 0), a2, voffA);
.Lrot_2132:
	ds_read_b128 v[142:145], v32
	ds_read_b128 v[148:151], v32 offset:1024
	ds_read_b128 v[158:161], v32 offset:2048
	ds_read_b128 v[168:171], v32 offset:3072
	v_add_u32_e32 v32, s43, v165
	ds_read_b128 v[172:175], v32
	ds_read_b128 v[176:179], v32 offset:1024
	ds_read_b128 v[180:183], v32 offset:2048
	ds_read_b128 v[184:187], v32 offset:3072
	v_lshl_add_u64 v[146:147], s[48:49], 0, v[138:139]
	s_add_i32 m0, s75, 0xc000
	ds_read_b128 v[188:191], v167
	ds_read_b128 v[192:195], v167 offset:1024
	ds_read_b128 v[196:199], v167 offset:2048
	ds_read_b128 v[208:211], v167 offset:3072
	ds_read_b128 v[216:219], v167 offset:4096
	ds_read_b128 v[220:223], v167 offset:5120
	ds_read_b128 v[224:227], v167 offset:6144
	ds_read_b128 v[228:231], v167 offset:7168
	global_load_lds_dwordx4 v[146:147], off
	v_lshl_add_u64 v[146:147], s[48:49], 0, v[140:141]
	s_add_i32 m0, s75, 0xe000
	s_nop 0
	global_load_lds_dwordx4 v[146:147], off
	s_waitcnt vmcnt(8)
	s_waitcnt lgkmcnt(0)
	s_barrier
	s_setprio 1
	s_waitcnt lgkmcnt(0)
	v_mfma_f32_16x16x32_bf16 v[126:129], v[142:145], v[188:191], v[126:129]
	v_mfma_f32_16x16x32_bf16 v[122:125], v[158:161], v[188:191], v[122:125]
	v_mfma_f32_16x16x32_bf16 v[110:113], v[142:145], v[196:199], v[110:113]
	v_mfma_f32_16x16x32_bf16 v[106:109], v[158:161], v[196:199], v[106:109]
	v_mfma_f32_16x16x32_bf16 v[94:97], v[142:145], v[216:219], v[94:97]
	v_mfma_f32_16x16x32_bf16 v[90:93], v[158:161], v[216:219], v[90:93]
	v_mfma_f32_16x16x32_bf16 v[78:81], v[142:145], v[224:227], v[78:81]
	v_mfma_f32_16x16x32_bf16 v[74:77], v[158:161], v[224:227], v[74:77]
	v_mfma_f32_16x16x32_bf16 v[126:129], v[148:151], v[192:195], v[126:129]
	v_mfma_f32_16x16x32_bf16 v[122:125], v[168:171], v[192:195], v[122:125]
	v_mfma_f32_16x16x32_bf16 v[110:113], v[148:151], v[208:211], v[110:113]
	v_mfma_f32_16x16x32_bf16 v[106:109], v[168:171], v[208:211], v[106:109]
	v_mfma_f32_16x16x32_bf16 v[94:97], v[148:151], v[220:223], v[94:97]
	v_mfma_f32_16x16x32_bf16 v[90:93], v[168:171], v[220:223], v[90:93]
	v_mfma_f32_16x16x32_bf16 v[78:81], v[148:151], v[228:231], v[78:81]
	v_mfma_f32_16x16x32_bf16 v[74:77], v[168:171], v[228:231], v[74:77]
	s_setprio 0
	s_setprio 1
	v_mfma_f32_16x16x32_bf16 v[118:121], v[172:175], v[188:191], v[118:121]
	v_mfma_f32_16x16x32_bf16 v[114:117], v[180:183], v[188:191], v[114:117]
	v_mfma_f32_16x16x32_bf16 v[102:105], v[172:175], v[196:199], v[102:105]
	v_mfma_f32_16x16x32_bf16 v[98:101], v[180:183], v[196:199], v[98:101]
	v_mfma_f32_16x16x32_bf16 v[86:89], v[172:175], v[216:219], v[86:89]
	v_mfma_f32_16x16x32_bf16 v[82:85], v[180:183], v[216:219], v[82:85]
	v_mfma_f32_16x16x32_bf16 v[70:73], v[172:175], v[224:227], v[70:73]
	v_mfma_f32_16x16x32_bf16 v[66:69], v[180:183], v[224:227], v[66:69]
	v_mfma_f32_16x16x32_bf16 v[118:121], v[176:179], v[192:195], v[118:121]
	v_mfma_f32_16x16x32_bf16 v[114:117], v[184:187], v[192:195], v[114:117]
	v_mfma_f32_16x16x32_bf16 v[102:105], v[176:179], v[208:211], v[102:105]
	v_mfma_f32_16x16x32_bf16 v[98:101], v[184:187], v[208:211], v[98:101]
	v_mfma_f32_16x16x32_bf16 v[86:89], v[176:179], v[220:223], v[86:89]
	v_mfma_f32_16x16x32_bf16 v[82:85], v[184:187], v[220:223], v[82:85]
	v_mfma_f32_16x16x32_bf16 v[70:73], v[176:179], v[228:231], v[70:73]
	v_mfma_f32_16x16x32_bf16 v[66:69], v[184:187], v[228:231], v[66:69]
	s_setprio 0
	s_barrier
	s_add_i32 s93, s93, s74
	v_lshl_add_u64 v[146:147], s[50:51], 0, v[132:133]
	s_mov_b32 m0, s93
	ds_read_b128 v[188:191], v167 offset:16384
	ds_read_b128 v[192:195], v167 offset:17408
	ds_read_b128 v[196:199], v167 offset:18432
	ds_read_b128 v[208:211], v167 offset:19456
	ds_read_b128 v[216:219], v167 offset:20480
	ds_read_b128 v[220:223], v167 offset:21504
	ds_read_b128 v[224:227], v167 offset:22528
	ds_read_b128 v[228:231], v167 offset:23552
	global_load_lds_dwordx4 v[146:147], off
	s_add_i32 m0, s93, 0x2000
	s_add_u32 s94, s50, 0x100000
	v_lshl_add_u64 v[162:163], s[50:51], 0, v[136:137]
	s_addc_u32 s95, s51, 0
	s_add_i32 s43, s43, s74
	global_load_lds_dwordx4 v[162:163], off
	v_lshl_add_u64 v[200:201], s[94:95], 0, v[132:133]
	s_mov_b32 m0, s43
	v_lshl_add_u64 v[204:205], s[52:53], 0, v[134:135]
	global_load_lds_dwordx4 v[200:201], off
	v_lshl_add_u64 v[200:201], s[94:95], 0, v[136:137]
	s_add_i32 m0, s43, 0x2000
	s_nop 0
	global_load_lds_dwordx4 v[200:201], off
	v_lshl_add_u64 v[200:201], s[52:53], 0, v[130:131]
	s_mov_b32 m0, s75
	s_nop 0
	global_load_lds_dwordx4 v[200:201], off
	s_mov_b32 m0, s76
	s_nop 0
	global_load_lds_dwordx4 v[204:205], off
	s_waitcnt vmcnt(8)
	s_waitcnt lgkmcnt(0)
	s_barrier
; #define PG8_STAGE(bufoff, gbase, voff) do { _Pragma("unroll") for (int _i = 0; _i < 2; ++_i) \
;         __builtin_amdgcn_global_load_lds((const unsigned*)((const char*)(gbase) + (voff)[_i]), (PG8_LAS unsigned*)(lds + (bufoff) + ldsw + _i * 8192), 16, 0, 0); } while (0)
; #define PG8_LDA(dst, b, h) do { _Pragma("unroll") for (int m = 0; m < 4; ++m) _Pragma("unroll") for (int k = 0; k < 2; ++k) dst[m][k] = *(const PG8_LAS bf16x8*)(lds + PG8_SA(b, h) + aoff + m * 2048 + k * 1024); } while (0)
; #define PG8_LDB(dst, b, h) do { _Pragma("unroll") for (int n = 0; n < 2; ++n) _Pragma("unroll") for (int k = 0; k < 2; ++k) dst[n][k] = *(const PG8_LAS bf16x8*)(lds + PG8_SB(b, h) + boff + n * 2048 + k * 1024); } while (0)
; #define PG8_WAIT_V(n) asm volatile("s_waitcnt vmcnt(" #n ")" ::: "memory")
; #define PG8_WAIT_L(n) asm volatile("s_waitcnt lgkmcnt(" #n ")" ::: "memory")
; #define PG8_BAR __builtin_amdgcn_s_barrier()
; #define PG8_SCHED __builtin_amdgcn_sched_barrier(0)
; template <class Epi, bool ALIGN_EPI = true>
; __device__ __forceinline__ void gemm_phase(PG8_LAS unsigned char* lds, const Gemm g, const StaticOrder& S, const Epi& E) {
;     ...
;             PG8_WAIT_V(8); PG8_WAIT_L(0); PG8_BAR; PG8_MMA(1, 0, At, B0); PG8_MMA(1, 1, At, B1); PG8_BAR; PG8_SCHED;
;             PG8_LDB(B0, 1, 0); PG8_LDB(B1, 1, 1); PG8_SCHED; PG8_LDA(At, 1, 0); PG8_STAGE(PG8_SA(0, 1), a2 + hstepA, voffA);
;             PG8_WAIT_V(8); PG8_WAIT_L(0); PG8_BAR; PG8_MMA(0, 0, At, B0); PG8_MMA(0, 1, At, B1); PG8_BAR; PG8_SCHED;
	s_setprio 1
	s_waitcnt lgkmcnt(0)
	v_mfma_f32_16x16x32_bf16 v[62:65], v[142:145], v[188:191], v[62:65]
	v_mfma_f32_16x16x32_bf16 v[58:61], v[158:161], v[188:191], v[58:61]
	v_mfma_f32_16x16x32_bf16 v[46:49], v[142:145], v[196:199], v[46:49]
	v_mfma_f32_16x16x32_bf16 v[42:45], v[158:161], v[196:199], v[42:45]
	v_mfma_f32_16x16x32_bf16 v[28:31], v[142:145], v[216:219], v[28:31]
	v_mfma_f32_16x16x32_bf16 v[24:27], v[158:161], v[216:219], v[24:27]
	v_mfma_f32_16x16x32_bf16 v[12:15], v[142:145], v[224:227], v[12:15]
	v_mfma_f32_16x16x32_bf16 v[8:11], v[158:161], v[224:227], v[8:11]
	v_mfma_f32_16x16x32_bf16 v[62:65], v[148:151], v[192:195], v[62:65]
	v_mfma_f32_16x16x32_bf16 v[58:61], v[168:171], v[192:195], v[58:61]
	v_mfma_f32_16x16x32_bf16 v[46:49], v[148:151], v[208:211], v[46:49]
	v_mfma_f32_16x16x32_bf16 v[42:45], v[168:171], v[208:211], v[42:45]
	v_mfma_f32_16x16x32_bf16 v[28:31], v[148:151], v[220:223], v[28:31]
	v_mfma_f32_16x16x32_bf16 v[24:27], v[168:171], v[220:223], v[24:27]
	v_mfma_f32_16x16x32_bf16 v[12:15], v[148:151], v[228:231], v[12:15]
	v_mfma_f32_16x16x32_bf16 v[8:11], v[168:171], v[228:231], v[8:11]
	s_setprio 0
	s_setprio 1
	v_mfma_f32_16x16x32_bf16 v[54:57], v[172:175], v[188:191], v[54:57]
	v_mfma_f32_16x16x32_bf16 v[50:53], v[180:183], v[188:191], v[50:53]
	v_mfma_f32_16x16x32_bf16 v[38:41], v[172:175], v[196:199], v[38:41]
	v_mfma_f32_16x16x32_bf16 v[34:37], v[180:183], v[196:199], v[34:37]
	v_mfma_f32_16x16x32_bf16 v[20:23], v[172:175], v[216:219], v[20:23]
	v_mfma_f32_16x16x32_bf16 v[16:19], v[180:183], v[216:219], v[16:19]
	v_mfma_f32_16x16x32_bf16 v[4:7], v[172:175], v[224:227], v[4:7]
	v_mfma_f32_16x16x32_bf16 v[0:3], v[180:183], v[224:227], v[0:3]
	v_mfma_f32_16x16x32_bf16 v[54:57], v[176:179], v[192:195], v[54:57]
	v_mfma_f32_16x16x32_bf16 v[50:53], v[184:187], v[192:195], v[50:53]
	v_mfma_f32_16x16x32_bf16 v[38:41], v[176:179], v[208:211], v[38:41]
	v_mfma_f32_16x16x32_bf16 v[34:37], v[184:187], v[208:211], v[34:37]
	v_mfma_f32_16x16x32_bf16 v[20:23], v[176:179], v[220:223], v[20:23]
	v_mfma_f32_16x16x32_bf16 v[16:19], v[184:187], v[220:223], v[16:19]
	v_mfma_f32_16x16x32_bf16 v[4:7], v[176:179], v[228:231], v[4:7]
	v_mfma_f32_16x16x32_bf16 v[0:3], v[184:187], v[228:231], v[0:3]
	s_setprio 0
	s_barrier
	s_add_i32 s43, 0, 0x18000
	v_add_u32_e32 v32, s43, v165
	s_add_i32 s93, 0, 0x1c000
	ds_read_b128 v[142:145], v32
	ds_read_b128 v[148:151], v32 offset:1024
	ds_read_b128 v[158:161], v32 offset:2048
	ds_read_b128 v[168:171], v32 offset:3072
	v_add_u32_e32 v32, s93, v165
	ds_read_b128 v[172:175], v32
	ds_read_b128 v[176:179], v32 offset:1024
	ds_read_b128 v[180:183], v32 offset:2048
	ds_read_b128 v[184:187], v32 offset:3072
	s_add_u32 s52, s52, 0x100000
	s_addc_u32 s53, s53, 0
	s_mov_b32 m0, s77
	v_lshl_add_u64 v[206:207], s[52:53], 0, v[130:131]
	ds_read_b128 v[188:191], v167 offset:32768
	ds_read_b128 v[192:195], v167 offset:33792
	ds_read_b128 v[196:199], v167 offset:34816
	ds_read_b128 v[208:211], v167 offset:35840
	ds_read_b128 v[216:219], v167 offset:36864
	ds_read_b128 v[220:223], v167 offset:37888
	ds_read_b128 v[224:227], v167 offset:38912
	ds_read_b128 v[228:231], v167 offset:39936
	global_load_lds_dwordx4 v[206:207], off
	v_lshl_add_u64 v[206:207], s[52:53], 0, v[134:135]
	s_mov_b32 m0, s82
	s_nop 0
	global_load_lds_dwordx4 v[206:207], off
	s_waitcnt vmcnt(8)
	s_waitcnt lgkmcnt(0)
	s_barrier
	s_setprio 1
	s_waitcnt lgkmcnt(0)
	v_mfma_f32_16x16x32_bf16 v[126:129], v[142:145], v[188:191], v[126:129]
	v_mfma_f32_16x16x32_bf16 v[122:125], v[158:161], v[188:191], v[122:125]
	v_mfma_f32_16x16x32_bf16 v[110:113], v[142:145], v[196:199], v[110:113]
	v_mfma_f32_16x16x32_bf16 v[106:109], v[158:161], v[196:199], v[106:109]
	v_mfma_f32_16x16x32_bf16 v[94:97], v[142:145], v[216:219], v[94:97]
	v_mfma_f32_16x16x32_bf16 v[90:93], v[158:161], v[216:219], v[90:93]
	v_mfma_f32_16x16x32_bf16 v[78:81], v[142:145], v[224:227], v[78:81]
	v_mfma_f32_16x16x32_bf16 v[74:77], v[158:161], v[224:227], v[74:77]
	v_mfma_f32_16x16x32_bf16 v[126:129], v[148:151], v[192:195], v[126:129]
	v_mfma_f32_16x16x32_bf16 v[122:125], v[168:171], v[192:195], v[122:125]
	v_mfma_f32_16x16x32_bf16 v[110:113], v[148:151], v[208:211], v[110:113]
	v_mfma_f32_16x16x32_bf16 v[106:109], v[168:171], v[208:211], v[106:109]
	v_mfma_f32_16x16x32_bf16 v[94:97], v[148:151], v[220:223], v[94:97]
	v_mfma_f32_16x16x32_bf16 v[90:93], v[168:171], v[220:223], v[90:93]
	v_mfma_f32_16x16x32_bf16 v[78:81], v[148:151], v[228:231], v[78:81]
	v_mfma_f32_16x16x32_bf16 v[74:77], v[168:171], v[228:231], v[74:77]
	s_setprio 0
	s_setprio 1
	v_mfma_f32_16x16x32_bf16 v[118:121], v[172:175], v[188:191], v[118:121]
	v_mfma_f32_16x16x32_bf16 v[114:117], v[180:183], v[188:191], v[114:117]
	v_mfma_f32_16x16x32_bf16 v[102:105], v[172:175], v[196:199], v[102:105]
	v_mfma_f32_16x16x32_bf16 v[98:101], v[180:183], v[196:199], v[98:101]
	v_mfma_f32_16x16x32_bf16 v[86:89], v[172:175], v[216:219], v[86:89]
	v_mfma_f32_16x16x32_bf16 v[82:85], v[180:183], v[216:219], v[82:85]
	v_mfma_f32_16x16x32_bf16 v[70:73], v[172:175], v[224:227], v[70:73]
	v_mfma_f32_16x16x32_bf16 v[66:69], v[180:183], v[224:227], v[66:69]
	v_mfma_f32_16x16x32_bf16 v[118:121], v[176:179], v[192:195], v[118:121]
	v_mfma_f32_16x16x32_bf16 v[114:117], v[184:187], v[192:195], v[114:117]
	v_mfma_f32_16x16x32_bf16 v[102:105], v[176:179], v[208:211], v[102:105]
	v_mfma_f32_16x16x32_bf16 v[98:101], v[184:187], v[208:211], v[98:101]
	v_mfma_f32_16x16x32_bf16 v[86:89], v[176:179], v[220:223], v[86:89]
	v_mfma_f32_16x16x32_bf16 v[82:85], v[184:187], v[220:223], v[82:85]
	v_mfma_f32_16x16x32_bf16 v[70:73], v[176:179], v[228:231], v[70:73]
	v_mfma_f32_16x16x32_bf16 v[66:69], v[184:187], v[228:231], v[66:69]
	s_setprio 0
	s_barrier
; #define PG8_STAGE(bufoff, gbase, voff) do { _Pragma("unroll") for (int _i = 0; _i < 2; ++_i) \
;         __builtin_amdgcn_global_load_lds((const unsigned*)((const char*)(gbase) + (voff)[_i]), (PG8_LAS unsigned*)(lds + (bufoff) + ldsw + _i * 8192), 16, 0, 0); } while (0)
; #define PG8_LDA(dst, b, h) do { _Pragma("unroll") for (int m = 0; m < 4; ++m) _Pragma("unroll") for (int k = 0; k < 2; ++k) dst[m][k] = *(const PG8_LAS bf16x8*)(lds + PG8_SA(b, h) + aoff + m * 2048 + k * 1024); } while (0)
; #define PG8_WAIT_V(n) asm volatile("s_waitcnt vmcnt(" #n ")" ::: "memory")
; #define PG8_WAIT_L(n) asm volatile("s_waitcnt lgkmcnt(" #n ")" ::: "memory")
; #define PG8_BAR __builtin_amdgcn_s_barrier()
; #define PG8_SCHED __builtin_amdgcn_sched_barrier(0)
; template <class Epi, bool ALIGN_EPI = true>
; __device__ __forceinline__ void gemm_phase(PG8_LAS unsigned char* lds, const Gemm g, const StaticOrder& S, const Epi& E) {
;     ...
;         for (int t = 0; t < nt; t += 2) {
;             const bool last = (t == nt - 2);
;             const char* a1 = cA + (size_t)(t + 1) * kstep;
;             const char* a2 = last ? nA : cA + (size_t)(t + 2) * kstep; const char* b2 = last ? nB : cB + (size_t)(t + 2) * kstep;
;     ...
;             PG8_LDA(At, 1, 1); PG8_STAGE(PG8_SB(1, 0), b3, voffB); PG8_STAGE(PG8_SB(1, 1), b3 + hstepB, voffB); PG8_STAGE(PG8_SA(1, 0), a3, voffA);
;             PG8_WAIT_V(8); PG8_WAIT_L(0); PG8_BAR; PG8_MMA(1, 0, At, B0); PG8_MMA(1, 1, At, B1); PG8_BAR; PG8_SCHED;
	s_add_i32 s43, s43, s74
	v_lshl_add_u64 v[146:147], v[146:147], 0, s[60:61]
	s_mov_b32 m0, s43
	ds_read_b128 v[188:191], v167 offset:49152
	ds_read_b128 v[192:195], v167 offset:50176
	ds_read_b128 v[196:199], v167 offset:51200
	ds_read_b128 v[208:211], v167 offset:52224
	ds_read_b128 v[216:219], v167 offset:53248
	ds_read_b128 v[220:223], v167 offset:54272
	ds_read_b128 v[224:227], v167 offset:55296
	ds_read_b128 v[228:231], v167 offset:56320
	global_load_lds_dwordx4 v[146:147], off
	s_add_i32 m0, s43, 0x2000
	s_add_u32 s50, s50, 0x100080
	v_lshl_add_u64 v[146:147], v[162:163], 0, s[60:61]
	s_addc_u32 s51, s51, 0
	s_add_i32 s43, s93, s74
	global_load_lds_dwordx4 v[146:147], off
	v_lshl_add_u64 v[146:147], s[50:51], 0, v[132:133]
	s_mov_b32 m0, s43
	s_nop 0
	global_load_lds_dwordx4 v[146:147], off
	v_lshl_add_u64 v[146:147], s[50:51], 0, v[136:137]
	s_add_i32 m0, s43, 0x2000
	s_nop 0
	global_load_lds_dwordx4 v[146:147], off
	v_lshl_add_u64 v[146:147], v[200:201], 0, s[60:61]
	s_mov_b32 m0, s83
	s_nop 0
	global_load_lds_dwordx4 v[146:147], off
	v_lshl_add_u64 v[146:147], v[204:205], 0, s[60:61]
	s_mov_b32 m0, s85
	s_nop 0
	global_load_lds_dwordx4 v[146:147], off
	s_add_i32 s41, s41, 2
	s_add_u32 s48, s48, 0x100
	s_addc_u32 s49, s49, 0
	s_add_u32 s7, s7, 0x100
	s_addc_u32 s9, s9, 0
	s_add_u32 s43, s48, 0xfff00080
	s_addc_u32 s50, s49, -1
	s_add_i32 s93, 0, 0x10000
	s_cmp_eq_u32 s41, 60
	s_cselect_b32 s53, s45, s50
	s_cselect_b32 s52, s44, s43
	v_add_u32_e32 v32, s93, v165
	s_cselect_b32 s51, s47, s9
	s_cselect_b32 s50, s46, s7
	s_add_i32 s43, 0, 0x14000
	s_cmp_gt_u32 s41, 61
	s_waitcnt vmcnt(8)
	s_waitcnt lgkmcnt(0)
	s_barrier
	s_setprio 1
	s_waitcnt lgkmcnt(0)
	v_mfma_f32_16x16x32_bf16 v[62:65], v[142:145], v[188:191], v[62:65]
	v_mfma_f32_16x16x32_bf16 v[58:61], v[158:161], v[188:191], v[58:61]
	v_mfma_f32_16x16x32_bf16 v[46:49], v[142:145], v[196:199], v[46:49]
	v_mfma_f32_16x16x32_bf16 v[42:45], v[158:161], v[196:199], v[42:45]
	v_mfma_f32_16x16x32_bf16 v[28:31], v[142:145], v[216:219], v[28:31]
	v_mfma_f32_16x16x32_bf16 v[24:27], v[158:161], v[216:219], v[24:27]
	v_mfma_f32_16x16x32_bf16 v[12:15], v[142:145], v[224:227], v[12:15]
	v_mfma_f32_16x16x32_bf16 v[8:11], v[158:161], v[224:227], v[8:11]
	v_mfma_f32_16x16x32_bf16 v[62:65], v[148:151], v[192:195], v[62:65]
	v_mfma_f32_16x16x32_bf16 v[58:61], v[168:171], v[192:195], v[58:61]
	v_mfma_f32_16x16x32_bf16 v[46:49], v[148:151], v[208:211], v[46:49]
	v_mfma_f32_16x16x32_bf16 v[42:45], v[168:171], v[208:211], v[42:45]
	v_mfma_f32_16x16x32_bf16 v[28:31], v[148:151], v[220:223], v[28:31]
	v_mfma_f32_16x16x32_bf16 v[24:27], v[168:171], v[220:223], v[24:27]
	v_mfma_f32_16x16x32_bf16 v[12:15], v[148:151], v[228:231], v[12:15]
	v_mfma_f32_16x16x32_bf16 v[8:11], v[168:171], v[228:231], v[8:11]
	s_setprio 0
	s_setprio 1
	v_mfma_f32_16x16x32_bf16 v[54:57], v[172:175], v[188:191], v[54:57]
	v_mfma_f32_16x16x32_bf16 v[50:53], v[180:183], v[188:191], v[50:53]
	v_mfma_f32_16x16x32_bf16 v[38:41], v[172:175], v[196:199], v[38:41]
	v_mfma_f32_16x16x32_bf16 v[34:37], v[180:183], v[196:199], v[34:37]
	v_mfma_f32_16x16x32_bf16 v[20:23], v[172:175], v[216:219], v[20:23]
	v_mfma_f32_16x16x32_bf16 v[16:19], v[180:183], v[216:219], v[16:19]
	v_mfma_f32_16x16x32_bf16 v[4:7], v[172:175], v[224:227], v[4:7]
	v_mfma_f32_16x16x32_bf16 v[0:3], v[180:183], v[224:227], v[0:3]
	v_mfma_f32_16x16x32_bf16 v[54:57], v[176:179], v[192:195], v[54:57]
	v_mfma_f32_16x16x32_bf16 v[50:53], v[184:187], v[192:195], v[50:53]
	v_mfma_f32_16x16x32_bf16 v[38:41], v[176:179], v[208:211], v[38:41]
	v_mfma_f32_16x16x32_bf16 v[34:37], v[184:187], v[208:211], v[34:37]
	v_mfma_f32_16x16x32_bf16 v[20:23], v[176:179], v[220:223], v[20:23]
	v_mfma_f32_16x16x32_bf16 v[16:19], v[184:187], v[220:223], v[16:19]
	v_mfma_f32_16x16x32_bf16 v[4:7], v[176:179], v[228:231], v[4:7]
	v_mfma_f32_16x16x32_bf16 v[0:3], v[184:187], v[228:231], v[0:3]
	s_setprio 0
	s_barrier
	s_cbranch_scc0 .Lrot_2132
	s_and_b64 vcc, exec, s[38:39]
	s_cbranch_vccz .LBB0_2135
	s_barrier
